# WY producer: wave 0 queue grab and decay/dt loads issued at task top and collected at use; next-task operand loads packed after the solve instead of being waited on right after issue
# baseline (speedup 1.0000x reference)
; #define LAS __attribute__((address_space(3)))
; __device__ __forceinline__ float bf2f(bf16 v) { return __uint_as_float(((unsigned)v) << 16); }
; __device__ __forceinline__ unsigned f2bf(float f) { unsigned u = __float_as_uint(f); return (u + 0x7fffu + ((u >> 16) & 1u)) >> 16; }
; __device__ __forceinline__ float siluf_(float x) { return x / (1.0f + __expf(-x)); }
; __device__ __forceinline__ int wy_producer_task(const Ctx& c, int l, int tk, WyPre& P, unsigned* head) {
;     LAS float* Lf = (LAS float*)c.lds; LAS float* KF = Lf + WY_KF; LAS float* QF = Lf + WY_QF; LAS float* LM = Lf + WY_LM; LAS float* KT = Lf + WY_KT; LAS float* GC = Lf + WY_GC; LAS float* BE = Lf + WY_BE;
;     LAS unsigned char* KIMG = c.lds + WY_KIMG_B;
;     int lane = c.lane; asm volatile("" : "+v"(lane));
;     const int wid = c.wave, r32 = lane & 31, hi = lane >> 5, q4 = lane & 3, cc = lane >> 2;
;     const int hh = tk & 7;
;     u32x4* PKm = (u32x4*)(AWS + WS_PK);
;     volatile LAS unsigned* slot = (volatile LAS unsigned*)(c.lds - CTLB + MISC_OFF + 64);
;     unsigned gnext = 0u;
;     if (wid == 0 && lane == 0) gnext = __hip_atomic_fetch_add(head, 1u, __ATOMIC_RELAXED, __HIP_MEMORY_SCOPE_AGENT);
;     LAS float* VF = Lf + WY_VF;
; #pragma unroll
;     for (int j = 0; j < 3; ++j) { float xv[11];
; #pragma unroll
;         for (int r = 0; r < 11; ++r) xv[r] = bf2f((bf16)P.hx[j][r]);
; #pragma unroll
;         for (int r = 0; r < 8; ++r) { const int i = 8 * wid + r;
;             float y = siluf_(P.cw[j][0] * xv[r] + P.cw[j][1] * xv[r + 1] + P.cw[j][2] * xv[r + 2] + P.cw[j][3] * xv[r + 3]);
;             if (j < 2) y *= rsqrtf(wave_sum_fast(y * y) + RMS_EPS) * (j == 0 ? 0.125f : 1.0f);
;             if (j == 0) QF[i * 65 + lane] = y;
;             else if (j == 1) { KF[i * 65 + lane] = y; *(LAS bf16*)(KIMG + (lane >> 3) * 1024 + i * 16 + (lane & 7) * 2) = (bf16)f2bf(y); }
;             else VF[i * 65 + lane] = y; } }
.LBB0_960:
	v_mov_b32_e32 v88, v82
	ds_read_b32 v0, v1 offset:464
	v_cmp_eq_u32_e64 s[40:41], 0, v88
	s_and_b64 s[4:5], s[44:45], s[40:41]
	s_waitcnt lgkmcnt(0)
	v_readfirstlane_b32 s0, v0
	ds_read_b32 v0, v1 offset:468
	s_waitcnt lgkmcnt(0)
	v_readfirstlane_b32 s10, v0
	v_mov_b32_e32 v0, 0
	s_andn2_b64 vcc, exec, s[44:45]
	s_cbranch_vccnz .Lwy_top_done
	ds_read_b32 v2, v1 offset:368
	ds_read_b32 v3, v1 offset:372
	ds_read_b32 v4, v1 offset:376
	ds_read_b32 v5, v1 offset:380
	s_and_b32 s1, s46, 7
	v_readlane_b32 s2, v254, 54
	s_nop 0
	s_or_b32 s30, s1, s2
	s_lshl_b64 s[2:3], s[30:31], 2
	s_waitcnt lgkmcnt(0)
	v_readfirstlane_b32 s6, v2
	v_readfirstlane_b32 s7, v3
	v_readfirstlane_b32 s8, v4
	v_readfirstlane_b32 s9, v5
	s_nop 0
	s_add_u32 s6, s6, s2
	s_addc_u32 s7, s7, s3
	s_add_u32 s8, s8, s2
	s_addc_u32 s9, s9, s3
	s_nop 4
	global_load_dword v249, v1, s[6:7]
	global_load_dword v250, v1, s[8:9]
	s_and_saveexec_b64 s[2:3], s[40:41]
	v_readlane_b32 s8, v255, 10
	v_readlane_b32 s9, v255, 11
	v_mov_b32_e32 v0, 1
	s_nop 4
	global_atomic_add v0, v1, v0, s[8:9] sc0
	s_or_b64 exec, exec, s[2:3]
.Lwy_top_done:
	v_lshlrev_b32_e32 v6, 16, v114
	v_and_b32_e32 v7, 0xffff0000, v114
	v_pk_mul_f32 v[8:9], v[84:85], v[6:7]
	v_and_b32_e32 v11, 0xffff0000, v89
	v_lshlrev_b32_e32 v10, 16, v89
	v_pk_mul_f32 v[12:13], v[86:87], v[10:11]
	v_add_f32_e32 v7, v8, v9
	v_add_f32_e32 v7, v13, v7
	v_add_f32_e32 v7, v12, v7
	v_mul_f32_e32 v8, 0xbfb8aa3b, v7
	v_exp_f32_e32 v8, v8
	v_lshlrev_b32_e32 v2, 2, v88
	s_add_i32 s1, 0, 0x11d00
	v_add_u32_e32 v3, 0, v2
	v_add_f32_e32 v8, 1.0, v8
	v_rcp_f32_e32 v9, v8
	v_add_u32_e32 v4, s1, v2
	v_lshlrev_b32_e32 v2, 7, v88
	v_lshlrev_b32_e32 v5, 1, v88
	s_nop 0
	v_mul_f32_e32 v7, v7, v9
	v_mul_f32_e32 v8, v7, v7
	v_and_b32_e32 v2, 0xfffffc00, v2
	v_and_b32_e32 v5, 14, v5
	v_mov_b32_dpp v8, v8 quad_perm:[1,0,3,2] row_mask:0xf bank_mask:0xf bound_ctrl:1
	v_fmac_f32_e32 v8, v7, v7
	v_readlane_b32 s1, v254, 32
	s_mov_b32 s7, 0x800000
	v_add_f32_dpp v8, v8, v8 quad_perm:[2,3,0,1] row_mask:0xf bank_mask:0xf bound_ctrl:1
	v_add3_u32 v5, s1, v2, v5
	v_and_b32_e32 v17, 0xffff0000, v115
	v_add_f32_dpp v8, v8, v8 row_half_mirror row_mask:0xf bank_mask:0xf bound_ctrl:1
	v_lshlrev_b32_e32 v16, 16, v115
	v_pk_mul_f32 v[14:15], v[84:85], v[10:11]
	v_add_f32_dpp v8, v8, v8 row_mirror row_mask:0xf bank_mask:0xf bound_ctrl:1
	v_lshlrev_b32_e32 v2, 16, v94
	v_readlane_b32 s1, v8, 16
	v_readlane_b32 s6, v8, 48
	v_readlane_b32 s2, v8, 0
	v_readlane_b32 s3, v8, 32
	v_mov_b32_e32 v8, s1
	v_mov_b32_e32 v9, s6
	v_pk_add_f32 v[8:9], s[2:3], v[8:9]
	s_nop 0
	v_add_f32_e32 v8, v8, v9
	v_add_f32_e32 v8, 0x358637bd, v8
	s_nop 0
	v_rsq_f32_e32 v8, v8
	s_nop 0
	v_mul_f32_e32 v8, 0x3e000000, v8
	v_mul_f32_e32 v7, v7, v8
	v_pk_mov_b32 v[12:13], v[10:11], v[6:7] op_sel:[1,0]
	v_pk_mov_b32 v[10:11], v[16:17], v[10:11] op_sel:[1,0]
	v_pk_mul_f32 v[12:13], v[84:85], v[12:13]
	v_add_u32_e32 v8, s96, v3
	v_add_u32_e32 v6, s97, v3
	v_pk_mul_f32 v[18:19], v[86:87], v[10:11]
	v_add_f32_e32 v3, v12, v13
	v_add_f32_e32 v3, v19, v3
	v_add_f32_e32 v3, v18, v3
	v_mul_f32_e32 v9, 0xbfb8aa3b, v3
	v_exp_f32_e32 v9, v9
	v_pk_mul_f32 v[10:11], v[84:85], v[10:11]
	v_add_f32_e32 v9, 1.0, v9
	v_rcp_f32_e32 v12, v9
	s_nop 0
	s_nop 0
	v_mul_f32_e32 v3, v3, v12
	v_mul_f32_e32 v9, v3, v3
	s_nop 1
	v_mov_b32_dpp v9, v9 quad_perm:[1,0,3,2] row_mask:0xf bank_mask:0xf bound_ctrl:1
	v_fmac_f32_e32 v9, v3, v3
	s_nop 1
	v_add_f32_dpp v9, v9, v9 quad_perm:[2,3,0,1] row_mask:0xf bank_mask:0xf bound_ctrl:1
	s_nop 1
	v_add_f32_dpp v9, v9, v9 row_half_mirror row_mask:0xf bank_mask:0xf bound_ctrl:1
	s_nop 1
	v_add_f32_dpp v9, v9, v9 row_mirror row_mask:0xf bank_mask:0xf bound_ctrl:1
	s_nop 0
	v_readlane_b32 s1, v9, 16
	v_readlane_b32 s6, v9, 48
	v_readlane_b32 s2, v9, 0
	v_readlane_b32 s3, v9, 32
	v_mov_b32_e32 v12, s1
	v_mov_b32_e32 v13, s6
	v_pk_add_f32 v[12:13], s[2:3], v[12:13]
	s_nop 0
	v_add_f32_e32 v9, v12, v13
	v_add_f32_e32 v9, 0x358637bd, v9
	s_nop 0
	v_rsq_f32_e32 v9, v9
	s_nop 0
	v_mul_f32_e32 v9, 0x3e000000, v9
	v_mul_f32_e32 v3, v3, v9
	v_pk_mul_f32 v[12:13], v[86:87], v[16:17]
	v_add_f32_e32 v9, v14, v15
	v_add_f32_e32 v9, v13, v9
	v_add_f32_e32 v9, v12, v9
	v_mul_f32_e32 v12, 0xbfb8aa3b, v9
	v_exp_f32_e32 v12, v12
	s_nop 0
	v_add_f32_e32 v12, 1.0, v12
	v_rcp_f32_e32 v13, v12
	s_nop 0
	s_nop 0
	v_mul_f32_e32 v9, v9, v13
	v_mul_f32_e32 v12, v9, v9
	v_and_b32_e32 v15, 0xffff0000, v116
	v_lshlrev_b32_e32 v14, 16, v116
	v_mov_b32_dpp v12, v12 quad_perm:[1,0,3,2] row_mask:0xf bank_mask:0xf bound_ctrl:1
	v_fmac_f32_e32 v12, v9, v9
	s_nop 1
	v_add_f32_dpp v12, v12, v12 quad_perm:[2,3,0,1] row_mask:0xf bank_mask:0xf bound_ctrl:1
	s_nop 1
	v_add_f32_dpp v12, v12, v12 row_half_mirror row_mask:0xf bank_mask:0xf bound_ctrl:1
	s_nop 1
	v_add_f32_dpp v12, v12, v12 row_mirror row_mask:0xf bank_mask:0xf bound_ctrl:1
	s_nop 0
	v_readlane_b32 s1, v12, 16
	v_readlane_b32 s6, v12, 48
	v_readlane_b32 s2, v12, 0
	v_readlane_b32 s3, v12, 32
	v_mov_b32_e32 v12, s1
	v_mov_b32_e32 v13, s6
	v_pk_add_f32 v[12:13], s[2:3], v[12:13]
	s_nop 0
	v_add_f32_e32 v12, v12, v13
	v_add_f32_e32 v12, 0x358637bd, v12
	s_nop 0
	v_rsq_f32_e32 v12, v12
	s_nop 0
	v_mul_f32_e32 v12, 0x3e000000, v12
	v_mul_f32_e32 v9, v9, v12
	v_add_u32_e32 v12, 0x4400, v6
	ds_write2_b32 v12, v3, v9 offset0:64 offset1:129
	v_pk_mul_f32 v[12:13], v[84:85], v[16:17]
	v_pk_mov_b32 v[16:17], v[14:15], v[16:17] op_sel:[1,0]
	v_add_f32_e32 v3, v10, v11
	v_pk_mul_f32 v[18:19], v[86:87], v[16:17]
	s_nop 0
	v_add_f32_e32 v3, v19, v3
	v_add_f32_e32 v3, v18, v3
	v_mul_f32_e32 v9, 0xbfb8aa3b, v3
	v_exp_f32_e32 v9, v9
	s_nop 0
	v_add_f32_e32 v9, 1.0, v9
; #define LAS __attribute__((address_space(3)))
; __device__ __forceinline__ float bf2f(bf16 v) { return __uint_as_float(((unsigned)v) << 16); }
; __device__ __forceinline__ unsigned f2bf(float f) { unsigned u = __float_as_uint(f); return (u + 0x7fffu + ((u >> 16) & 1u)) >> 16; }
; __device__ __forceinline__ float siluf_(float x) { return x / (1.0f + __expf(-x)); }
; __device__ __forceinline__ int wy_producer_task(const Ctx& c, int l, int tk, WyPre& P, unsigned* head) {
;     ...
;     for (int j = 0; j < 3; ++j) { float xv[11];
; #pragma unroll
;         for (int r = 0; r < 11; ++r) xv[r] = bf2f((bf16)P.hx[j][r]);
; #pragma unroll
;         for (int r = 0; r < 8; ++r) { const int i = 8 * wid + r;
;             float y = siluf_(P.cw[j][0] * xv[r] + P.cw[j][1] * xv[r + 1] + P.cw[j][2] * xv[r + 2] + P.cw[j][3] * xv[r + 3]);
;             if (j < 2) y *= rsqrtf(wave_sum_fast(y * y) + RMS_EPS) * (j == 0 ? 0.125f : 1.0f);
;             if (j == 0) QF[i * 65 + lane] = y;
;             else if (j == 1) { KF[i * 65 + lane] = y; *(LAS bf16*)(KIMG + (lane >> 3) * 1024 + i * 16 + (lane & 7) * 2) = (bf16)f2bf(y); }
;             else VF[i * 65 + lane] = y; } }
	v_rcp_f32_e32 v10, v9
	s_nop 0
	s_nop 0
	v_mul_f32_e32 v3, v3, v10
	v_mul_f32_e32 v9, v3, v3
	s_nop 1
	v_mov_b32_dpp v9, v9 quad_perm:[1,0,3,2] row_mask:0xf bank_mask:0xf bound_ctrl:1
	v_fmac_f32_e32 v9, v3, v3
	s_nop 1
	v_add_f32_dpp v9, v9, v9 quad_perm:[2,3,0,1] row_mask:0xf bank_mask:0xf bound_ctrl:1
	s_nop 1
	v_add_f32_dpp v9, v9, v9 row_half_mirror row_mask:0xf bank_mask:0xf bound_ctrl:1
	s_nop 1
	v_add_f32_dpp v9, v9, v9 row_mirror row_mask:0xf bank_mask:0xf bound_ctrl:1
	s_nop 0
	v_readlane_b32 s1, v9, 16
	v_readlane_b32 s6, v9, 48
	v_readlane_b32 s2, v9, 0
	v_readlane_b32 s3, v9, 32
	v_mov_b32_e32 v10, s1
	v_mov_b32_e32 v11, s6
	v_pk_add_f32 v[10:11], s[2:3], v[10:11]
	s_nop 0
	v_add_f32_e32 v9, v10, v11
	v_add_f32_e32 v9, 0x358637bd, v9
	s_nop 0
	v_rsq_f32_e32 v9, v9
	s_nop 0
	v_mul_f32_e32 v9, 0x3e000000, v9
	v_mul_f32_e32 v3, v3, v9
	v_pk_mul_f32 v[10:11], v[86:87], v[14:15]
	v_add_f32_e32 v9, v12, v13
	v_add_f32_e32 v9, v11, v9
	v_add_f32_e32 v9, v10, v9
	v_mul_f32_e32 v10, 0xbfb8aa3b, v9
	v_exp_f32_e32 v10, v10
	s_nop 0
	v_add_f32_e32 v10, 1.0, v10
	v_rcp_f32_e32 v11, v10
	s_nop 0
	s_nop 0
	v_mul_f32_e32 v9, v9, v11
	v_mul_f32_e32 v10, v9, v9
	v_pk_mul_f32 v[12:13], v[84:85], v[14:15]
	s_nop 0
	v_mov_b32_dpp v10, v10 quad_perm:[1,0,3,2] row_mask:0xf bank_mask:0xf bound_ctrl:1
	v_fmac_f32_e32 v10, v9, v9
	s_nop 1
	v_add_f32_dpp v10, v10, v10 quad_perm:[2,3,0,1] row_mask:0xf bank_mask:0xf bound_ctrl:1
	s_nop 1
	v_add_f32_dpp v10, v10, v10 row_half_mirror row_mask:0xf bank_mask:0xf bound_ctrl:1
	s_nop 1
	v_add_f32_dpp v10, v10, v10 row_mirror row_mask:0xf bank_mask:0xf bound_ctrl:1
	s_nop 0
	v_readlane_b32 s1, v10, 16
	v_readlane_b32 s6, v10, 48
	v_readlane_b32 s2, v10, 0
	v_readlane_b32 s3, v10, 32
	v_mov_b32_e32 v10, s1
	v_mov_b32_e32 v11, s6
	v_pk_add_f32 v[10:11], s[2:3], v[10:11]
	s_nop 0
	v_add_f32_e32 v10, v10, v11
	v_add_f32_e32 v10, 0x358637bd, v10
	s_nop 0
	v_rsq_f32_e32 v10, v10
	s_nop 0
	v_mul_f32_e32 v10, 0x3e000000, v10
	v_mul_f32_e32 v9, v9, v10
	v_add_u32_e32 v10, 0x4600, v6
	ds_write2_b32 v10, v3, v9 offset0:66 offset1:131
	v_pk_mul_f32 v[10:11], v[84:85], v[16:17]
	v_and_b32_e32 v17, 0xffff0000, v117
	v_lshlrev_b32_e32 v16, 16, v117
	v_pk_mov_b32 v[14:15], v[16:17], v[14:15] op_sel:[1,0]
	v_add_f32_e32 v3, v10, v11
	v_pk_mul_f32 v[18:19], v[86:87], v[14:15]
	s_nop 0
	v_add_f32_e32 v3, v19, v3
	v_add_f32_e32 v3, v18, v3
	v_mul_f32_e32 v9, 0xbfb8aa3b, v3
	v_exp_f32_e32 v9, v9
	s_nop 0
	v_add_f32_e32 v9, 1.0, v9
	v_rcp_f32_e32 v10, v9
	s_nop 0
	s_nop 0
	v_mul_f32_e32 v3, v3, v10
	v_mul_f32_e32 v9, v3, v3
	s_nop 1
	v_mov_b32_dpp v9, v9 quad_perm:[1,0,3,2] row_mask:0xf bank_mask:0xf bound_ctrl:1
	v_fmac_f32_e32 v9, v3, v3
	s_nop 1
	v_add_f32_dpp v9, v9, v9 quad_perm:[2,3,0,1] row_mask:0xf bank_mask:0xf bound_ctrl:1
	s_nop 1
	v_add_f32_dpp v9, v9, v9 row_half_mirror row_mask:0xf bank_mask:0xf bound_ctrl:1
	s_nop 1
	v_add_f32_dpp v9, v9, v9 row_mirror row_mask:0xf bank_mask:0xf bound_ctrl:1
	s_nop 0
	v_readlane_b32 s1, v9, 16
	v_readlane_b32 s6, v9, 48
	v_readlane_b32 s2, v9, 0
	v_readlane_b32 s3, v9, 32
	v_mov_b32_e32 v10, s1
	v_mov_b32_e32 v11, s6
	v_pk_add_f32 v[10:11], s[2:3], v[10:11]
	s_nop 0
	v_add_f32_e32 v9, v10, v11
	v_add_f32_e32 v9, 0x358637bd, v9
	s_nop 0
	v_rsq_f32_e32 v9, v9
	s_nop 0
	v_mul_f32_e32 v9, 0x3e000000, v9
	v_mul_f32_e32 v3, v3, v9
	v_pk_mul_f32 v[10:11], v[86:87], v[16:17]
	v_add_f32_e32 v9, v12, v13
	v_add_f32_e32 v9, v11, v9
	v_add_f32_e32 v9, v10, v9
	v_mul_f32_e32 v10, 0xbfb8aa3b, v9
	v_exp_f32_e32 v10, v10
	s_nop 0
	v_add_f32_e32 v10, 1.0, v10
	v_rcp_f32_e32 v11, v10
	s_nop 0
	s_nop 0
	v_mul_f32_e32 v9, v9, v11
	v_mul_f32_e32 v10, v9, v9
	s_nop 1
	v_mov_b32_dpp v10, v10 quad_perm:[1,0,3,2] row_mask:0xf bank_mask:0xf bound_ctrl:1
	v_fmac_f32_e32 v10, v9, v9
	s_nop 1
	v_add_f32_dpp v10, v10, v10 quad_perm:[2,3,0,1] row_mask:0xf bank_mask:0xf bound_ctrl:1
	s_nop 1
	v_add_f32_dpp v10, v10, v10 row_half_mirror row_mask:0xf bank_mask:0xf bound_ctrl:1
	s_nop 1
	v_add_f32_dpp v10, v10, v10 row_mirror row_mask:0xf bank_mask:0xf bound_ctrl:1
	s_nop 0
	v_readlane_b32 s1, v10, 16
	v_readlane_b32 s6, v10, 48
	v_readlane_b32 s2, v10, 0
	v_readlane_b32 s3, v10, 32
	v_mov_b32_e32 v10, s1
	v_mov_b32_e32 v11, s6
	v_pk_add_f32 v[10:11], s[2:3], v[10:11]
	s_nop 0
	v_add_f32_e32 v10, v10, v11
	v_add_f32_e32 v10, 0x358637bd, v10
	s_nop 0
	v_rsq_f32_e32 v10, v10
	s_nop 0
	v_mul_f32_e32 v10, 0x3e000000, v10
	v_mul_f32_e32 v9, v9, v10
	v_add_u32_e32 v10, 0x4800, v6
	ds_write2_b32 v10, v3, v9 offset0:68 offset1:133
	v_pk_mul_f32 v[10:11], v[84:85], v[14:15]
	v_mov_b32_e32 v3, v16
	v_pk_mul_f32 v[2:3], v[86:87], v[2:3]
	v_add_f32_e32 v9, v10, v11
	v_add_f32_e32 v3, v3, v9
	v_add_f32_e32 v2, v2, v3
	v_mul_f32_e32 v3, 0xbfb8aa3b, v2
	v_exp_f32_e32 v3, v3
	v_and_b32_e32 v15, 0xffff0000, v118
	v_lshlrev_b32_e32 v14, 16, v118
	s_waitcnt vmcnt(4)
; #define LAS __attribute__((address_space(3)))
; __device__ __forceinline__ float bf2f(bf16 v) { return __uint_as_float(((unsigned)v) << 16); }
; __device__ __forceinline__ unsigned f2bf(float f) { unsigned u = __float_as_uint(f); return (u + 0x7fffu + ((u >> 16) & 1u)) >> 16; }
; __device__ __forceinline__ float siluf_(float x) { return x / (1.0f + __expf(-x)); }
; __device__ __forceinline__ int wy_producer_task(const Ctx& c, int l, int tk, WyPre& P, unsigned* head) {
;     ...
;     for (int j = 0; j < 3; ++j) { float xv[11];
; #pragma unroll
;         for (int r = 0; r < 11; ++r) xv[r] = bf2f((bf16)P.hx[j][r]);
; #pragma unroll
;         for (int r = 0; r < 8; ++r) { const int i = 8 * wid + r;
;             float y = siluf_(P.cw[j][0] * xv[r] + P.cw[j][1] * xv[r + 1] + P.cw[j][2] * xv[r + 2] + P.cw[j][3] * xv[r + 3]);
;             if (j < 2) y *= rsqrtf(wave_sum_fast(y * y) + RMS_EPS) * (j == 0 ? 0.125f : 1.0f);
;             if (j == 0) QF[i * 65 + lane] = y;
;             else if (j == 1) { KF[i * 65 + lane] = y; *(LAS bf16*)(KIMG + (lane >> 3) * 1024 + i * 16 + (lane & 7) * 2) = (bf16)f2bf(y); }
;             else VF[i * 65 + lane] = y; } }
	v_pk_mul_f32 v[16:17], v[92:93], v[14:15]
	v_add_f32_e32 v3, 1.0, v3
	v_rcp_f32_e32 v9, v3
	s_nop 0
	s_nop 0
	v_mul_f32_e32 v9, v2, v9
	v_mul_f32_e32 v2, v9, v9
	v_lshlrev_b32_e32 v10, 16, v119
	v_and_b32_e32 v11, 0xffff0000, v119
	v_mov_b32_dpp v2, v2 quad_perm:[1,0,3,2] row_mask:0xf bank_mask:0xf bound_ctrl:1
	v_fmac_f32_e32 v2, v9, v9
	v_pk_mul_f32 v[12:13], v[90:91], v[10:11]
	s_nop 0
	v_add_f32_dpp v2, v2, v2 quad_perm:[2,3,0,1] row_mask:0xf bank_mask:0xf bound_ctrl:1
	s_nop 1
	v_add_f32_dpp v2, v2, v2 row_half_mirror row_mask:0xf bank_mask:0xf bound_ctrl:1
	s_nop 1
	v_add_f32_dpp v2, v2, v2 row_mirror row_mask:0xf bank_mask:0xf bound_ctrl:1
	s_nop 0
	v_readlane_b32 s1, v2, 16
	v_readlane_b32 s6, v2, 48
	v_readlane_b32 s2, v2, 0
	v_readlane_b32 s3, v2, 32
	v_mov_b32_e32 v2, s1
	v_mov_b32_e32 v3, s6
	v_pk_add_f32 v[2:3], s[2:3], v[2:3]
	s_nop 0
	v_add_f32_e32 v2, v2, v3
	v_add_f32_e32 v2, 0x358637bd, v2
	s_nop 0
	v_rsq_f32_e32 v2, v2
	s_nop 0
	v_add_f32_e32 v3, v12, v13
	v_add_f32_e32 v3, v17, v3
	v_mul_f32_e32 v2, 0x3e000000, v2
	v_add_f32_e32 v3, v16, v3
	v_mul_f32_e32 v2, v9, v2
	v_mul_f32_e32 v9, 0xbfb8aa3b, v3
	v_exp_f32_e32 v9, v9
	ds_write_b32 v6, v2 offset:19224
	v_lshlrev_b32_e32 v2, 16, v96
	v_add_f32_e32 v9, 1.0, v9
	v_rcp_f32_e32 v11, v9
	s_nop 0
	s_nop 0
	v_mul_f32_e32 v3, v3, v11
	v_mul_f32_e32 v9, v3, v3
	s_nop 1
	v_mov_b32_dpp v9, v9 quad_perm:[1,0,3,2] row_mask:0xf bank_mask:0xf bound_ctrl:1
	v_fmac_f32_e32 v9, v3, v3
	s_nop 1
	v_add_f32_dpp v9, v9, v9 quad_perm:[2,3,0,1] row_mask:0xf bank_mask:0xf bound_ctrl:1
	s_nop 1
	v_add_f32_dpp v9, v9, v9 row_half_mirror row_mask:0xf bank_mask:0xf bound_ctrl:1
	s_nop 1
	v_add_f32_dpp v9, v9, v9 row_mirror row_mask:0xf bank_mask:0xf bound_ctrl:1
	s_nop 0
	v_readlane_b32 s1, v9, 16
	v_readlane_b32 s6, v9, 48
	v_readlane_b32 s2, v9, 0
	v_readlane_b32 s3, v9, 32
	v_mov_b32_e32 v12, s1
	v_mov_b32_e32 v13, s6
	v_pk_add_f32 v[12:13], s[2:3], v[12:13]
	s_nop 0
	v_add_f32_e32 v9, v12, v13
	v_add_f32_e32 v9, 0x358637bd, v9
	v_and_b32_e32 v13, 0xffff0000, v120
	v_rsq_f32_e32 v9, v9
	v_lshlrev_b32_e32 v12, 16, v120
	v_mul_f32_e32 v3, v3, v9
	ds_write2st64_b32 v8, v3, v7 offset0:4 offset1:69
	v_bfe_u32 v7, v3, 16, 1
	v_pk_mov_b32 v[8:9], v[14:15], v[10:11] op_sel:[1,0]
	v_add3_u32 v3, v3, v7, s15
	v_add_u32_e32 v7, s88, v5
	v_pk_mul_f32 v[8:9], v[90:91], v[8:9]
	v_pk_mul_f32 v[10:11], v[90:91], v[14:15]
	v_pk_mov_b32 v[14:15], v[12:13], v[14:15] op_sel:[1,0]
	ds_write_b16_d16_hi v7, v3
	v_pk_mul_f32 v[16:17], v[92:93], v[14:15]
	v_add_f32_e32 v7, v8, v9
	v_add_f32_e32 v7, v17, v7
	v_add_f32_e32 v7, v16, v7
	v_mul_f32_e32 v8, 0xbfb8aa3b, v7
	v_exp_f32_e32 v8, v8
	v_add_u32_e32 v3, s60, v5
	v_add_f32_e32 v8, 1.0, v8
	v_rcp_f32_e32 v9, v8
	s_nop 0
	s_nop 0
	v_mul_f32_e32 v7, v7, v9
	v_mul_f32_e32 v8, v7, v7
	v_add_u32_e32 v18, 0x400, v6
	s_nop 0
	v_mov_b32_dpp v8, v8 quad_perm:[1,0,3,2] row_mask:0xf bank_mask:0xf bound_ctrl:1
	v_fmac_f32_e32 v8, v7, v7
	s_nop 1
	v_add_f32_dpp v8, v8, v8 quad_perm:[2,3,0,1] row_mask:0xf bank_mask:0xf bound_ctrl:1
	s_nop 1
	v_add_f32_dpp v8, v8, v8 row_half_mirror row_mask:0xf bank_mask:0xf bound_ctrl:1
	s_nop 1
	v_add_f32_dpp v8, v8, v8 row_mirror row_mask:0xf bank_mask:0xf bound_ctrl:1
	s_nop 0
	v_readlane_b32 s1, v8, 16
	v_readlane_b32 s6, v8, 48
	v_readlane_b32 s2, v8, 0
	v_readlane_b32 s3, v8, 32
	v_mov_b32_e32 v8, s1
	v_mov_b32_e32 v9, s6
	v_pk_add_f32 v[8:9], s[2:3], v[8:9]
	s_nop 0
	v_add_f32_e32 v8, v8, v9
	v_add_f32_e32 v8, 0x358637bd, v8
	s_nop 0
	v_rsq_f32_e32 v8, v8
	s_nop 0
	v_mul_f32_e32 v7, v7, v8
	v_bfe_u32 v8, v7, 16, 1
	v_add3_u32 v8, v7, v8, s15
	ds_write_b16_d16_hi v3, v8
	v_pk_mul_f32 v[8:9], v[92:93], v[12:13]
	v_add_f32_e32 v3, v10, v11
	v_add_f32_e32 v3, v9, v3
	v_add_f32_e32 v3, v8, v3
	v_mul_f32_e32 v8, 0xbfb8aa3b, v3
	v_exp_f32_e32 v8, v8
	s_nop 0
	v_add_f32_e32 v8, 1.0, v8
	v_rcp_f32_e32 v9, v8
	s_nop 0
	s_nop 0
	v_mul_f32_e32 v3, v3, v9
	v_mul_f32_e32 v8, v3, v3
	v_pk_mul_f32 v[10:11], v[90:91], v[12:13]
	s_nop 0
	v_mov_b32_dpp v8, v8 quad_perm:[1,0,3,2] row_mask:0xf bank_mask:0xf bound_ctrl:1
	v_fmac_f32_e32 v8, v3, v3
	s_nop 1
	v_add_f32_dpp v8, v8, v8 quad_perm:[2,3,0,1] row_mask:0xf bank_mask:0xf bound_ctrl:1
	s_nop 1
	v_add_f32_dpp v8, v8, v8 row_half_mirror row_mask:0xf bank_mask:0xf bound_ctrl:1
	s_nop 1
	v_add_f32_dpp v8, v8, v8 row_mirror row_mask:0xf bank_mask:0xf bound_ctrl:1
	s_nop 0
	v_readlane_b32 s1, v8, 16
	v_readlane_b32 s6, v8, 48
	v_readlane_b32 s2, v8, 0
	v_readlane_b32 s3, v8, 32
	v_mov_b32_e32 v8, s1
	v_mov_b32_e32 v9, s6
	v_pk_add_f32 v[8:9], s[2:3], v[8:9]
	s_nop 0
	v_add_f32_e32 v8, v8, v9
	v_add_f32_e32 v8, 0x358637bd, v8
	s_nop 0
	v_rsq_f32_e32 v8, v8
	s_nop 0
	v_mul_f32_e32 v3, v3, v8
	ds_write2_b32 v18, v7, v3 offset1:65
	v_bfe_u32 v7, v3, 16, 1
	v_pk_mul_f32 v[8:9], v[90:91], v[14:15]
	v_and_b32_e32 v15, 0xffff0000, v121
	v_lshlrev_b32_e32 v14, 16, v121
	v_add3_u32 v3, v3, v7, s15
	v_add_u32_e32 v7, s61, v5
	v_pk_mov_b32 v[12:13], v[14:15], v[12:13] op_sel:[1,0]
	ds_write_b16_d16_hi v7, v3
	v_pk_mul_f32 v[16:17], v[92:93], v[12:13]
	v_add_f32_e32 v7, v8, v9
	v_add_f32_e32 v7, v17, v7
	v_add_f32_e32 v7, v16, v7
	v_mul_f32_e32 v8, 0xbfb8aa3b, v7
	v_exp_f32_e32 v8, v8
	v_add_u32_e32 v3, s91, v5
	v_add_f32_e32 v8, 1.0, v8
	v_rcp_f32_e32 v9, v8
	s_nop 0
	s_nop 0
	v_mul_f32_e32 v7, v7, v9
	v_mul_f32_e32 v8, v7, v7
	s_nop 1
	v_mov_b32_dpp v8, v8 quad_perm:[1,0,3,2] row_mask:0xf bank_mask:0xf bound_ctrl:1
	v_fmac_f32_e32 v8, v7, v7
	s_nop 1
	v_add_f32_dpp v8, v8, v8 quad_perm:[2,3,0,1] row_mask:0xf bank_mask:0xf bound_ctrl:1
	s_nop 1
	v_add_f32_dpp v8, v8, v8 row_half_mirror row_mask:0xf bank_mask:0xf bound_ctrl:1
; #define LAS __attribute__((address_space(3)))
; __device__ __forceinline__ float bf2f(bf16 v) { return __uint_as_float(((unsigned)v) << 16); }
; __device__ __forceinline__ unsigned f2bf(float f) { unsigned u = __float_as_uint(f); return (u + 0x7fffu + ((u >> 16) & 1u)) >> 16; }
; __device__ __forceinline__ float siluf_(float x) { return x / (1.0f + __expf(-x)); }
; __device__ __forceinline__ int wy_producer_task(const Ctx& c, int l, int tk, WyPre& P, unsigned* head) {
;     ...
;     for (int j = 0; j < 3; ++j) { float xv[11];
; #pragma unroll
;         for (int r = 0; r < 11; ++r) xv[r] = bf2f((bf16)P.hx[j][r]);
; #pragma unroll
;         for (int r = 0; r < 8; ++r) { const int i = 8 * wid + r;
;             float y = siluf_(P.cw[j][0] * xv[r] + P.cw[j][1] * xv[r + 1] + P.cw[j][2] * xv[r + 2] + P.cw[j][3] * xv[r + 3]);
;             if (j < 2) y *= rsqrtf(wave_sum_fast(y * y) + RMS_EPS) * (j == 0 ? 0.125f : 1.0f);
;             if (j == 0) QF[i * 65 + lane] = y;
;             else if (j == 1) { KF[i * 65 + lane] = y; *(LAS bf16*)(KIMG + (lane >> 3) * 1024 + i * 16 + (lane & 7) * 2) = (bf16)f2bf(y); }
;             else VF[i * 65 + lane] = y; } }
	s_nop 1
	v_add_f32_dpp v8, v8, v8 row_mirror row_mask:0xf bank_mask:0xf bound_ctrl:1
	s_nop 0
	v_readlane_b32 s1, v8, 16
	v_readlane_b32 s6, v8, 48
	v_readlane_b32 s2, v8, 0
	v_readlane_b32 s3, v8, 32
	v_mov_b32_e32 v8, s1
	v_mov_b32_e32 v9, s6
	v_pk_add_f32 v[8:9], s[2:3], v[8:9]
	s_nop 0
	v_add_f32_e32 v8, v8, v9
	v_add_f32_e32 v8, 0x358637bd, v8
	s_nop 0
	v_rsq_f32_e32 v8, v8
	s_nop 0
	v_mul_f32_e32 v7, v7, v8
	v_bfe_u32 v8, v7, 16, 1
	v_add3_u32 v8, v7, v8, s15
	ds_write_b16_d16_hi v3, v8
	v_pk_mul_f32 v[8:9], v[92:93], v[14:15]
	v_add_f32_e32 v3, v10, v11
	v_add_f32_e32 v3, v9, v3
	v_add_f32_e32 v3, v8, v3
	v_mul_f32_e32 v8, 0xbfb8aa3b, v3
	v_exp_f32_e32 v8, v8
	s_nop 0
	v_add_f32_e32 v8, 1.0, v8
	v_rcp_f32_e32 v9, v8
	s_nop 0
	s_nop 0
	v_mul_f32_e32 v3, v3, v9
	v_mul_f32_e32 v8, v3, v3
	v_pk_mul_f32 v[10:11], v[90:91], v[14:15]
	s_nop 0
	v_mov_b32_dpp v8, v8 quad_perm:[1,0,3,2] row_mask:0xf bank_mask:0xf bound_ctrl:1
	v_fmac_f32_e32 v8, v3, v3
	s_nop 1
	v_add_f32_dpp v8, v8, v8 quad_perm:[2,3,0,1] row_mask:0xf bank_mask:0xf bound_ctrl:1
	s_nop 1
	v_add_f32_dpp v8, v8, v8 row_half_mirror row_mask:0xf bank_mask:0xf bound_ctrl:1
	s_nop 1
	v_add_f32_dpp v8, v8, v8 row_mirror row_mask:0xf bank_mask:0xf bound_ctrl:1
	s_nop 0
	v_readlane_b32 s1, v8, 16
	v_readlane_b32 s6, v8, 48
	v_readlane_b32 s2, v8, 0
	v_readlane_b32 s3, v8, 32
	v_mov_b32_e32 v8, s1
	v_mov_b32_e32 v9, s6
	v_pk_add_f32 v[8:9], s[2:3], v[8:9]
	s_nop 0
	v_add_f32_e32 v8, v8, v9
	v_add_f32_e32 v8, 0x358637bd, v8
	s_nop 0
	v_rsq_f32_e32 v8, v8
	s_nop 0
	v_mul_f32_e32 v3, v3, v8
	ds_write2_b32 v18, v7, v3 offset0:130 offset1:195
	v_bfe_u32 v7, v3, 16, 1
	v_pk_mul_f32 v[8:9], v[90:91], v[12:13]
	v_and_b32_e32 v13, 0xffff0000, v122
	v_lshlrev_b32_e32 v12, 16, v122
	v_add3_u32 v3, v3, v7, s15
	v_add_u32_e32 v7, s92, v5
	v_pk_mov_b32 v[14:15], v[12:13], v[14:15] op_sel:[1,0]
	ds_write_b16_d16_hi v7, v3
	v_pk_mul_f32 v[16:17], v[92:93], v[14:15]
	v_add_f32_e32 v7, v8, v9
	v_add_f32_e32 v7, v17, v7
	v_add_f32_e32 v7, v16, v7
	v_mul_f32_e32 v8, 0xbfb8aa3b, v7
	v_exp_f32_e32 v8, v8
	v_add_u32_e32 v3, s62, v5
	v_add_f32_e32 v8, 1.0, v8
	v_rcp_f32_e32 v9, v8
	s_nop 0
	s_nop 0
	v_mul_f32_e32 v7, v7, v9
	v_mul_f32_e32 v8, v7, v7
	s_nop 1
	v_mov_b32_dpp v8, v8 quad_perm:[1,0,3,2] row_mask:0xf bank_mask:0xf bound_ctrl:1
	v_fmac_f32_e32 v8, v7, v7
	s_nop 1
	v_add_f32_dpp v8, v8, v8 quad_perm:[2,3,0,1] row_mask:0xf bank_mask:0xf bound_ctrl:1
	s_nop 1
	v_add_f32_dpp v8, v8, v8 row_half_mirror row_mask:0xf bank_mask:0xf bound_ctrl:1
	s_nop 1
	v_add_f32_dpp v8, v8, v8 row_mirror row_mask:0xf bank_mask:0xf bound_ctrl:1
	s_nop 0
	v_readlane_b32 s1, v8, 16
	v_readlane_b32 s6, v8, 48
	v_readlane_b32 s2, v8, 0
	v_readlane_b32 s3, v8, 32
	v_mov_b32_e32 v8, s1
	v_mov_b32_e32 v9, s6
	v_pk_add_f32 v[8:9], s[2:3], v[8:9]
	s_nop 0
	v_add_f32_e32 v8, v8, v9
	v_add_f32_e32 v8, 0x358637bd, v8
	s_nop 0
	v_rsq_f32_e32 v8, v8
	s_nop 0
	v_mul_f32_e32 v7, v7, v8
	v_bfe_u32 v8, v7, 16, 1
	v_add3_u32 v8, v7, v8, s15
	ds_write_b16_d16_hi v3, v8
	v_pk_mul_f32 v[8:9], v[92:93], v[12:13]
	v_add_f32_e32 v3, v10, v11
	v_add_f32_e32 v3, v9, v3
	v_add_f32_e32 v3, v8, v3
	v_mul_f32_e32 v8, 0xbfb8aa3b, v3
	v_exp_f32_e32 v8, v8
	s_nop 0
	v_add_f32_e32 v8, 1.0, v8
	v_rcp_f32_e32 v9, v8
	s_nop 0
	s_nop 0
	v_mul_f32_e32 v3, v3, v9
	v_mul_f32_e32 v8, v3, v3
	v_lshlrev_b32_e32 v13, 16, v104
	s_nop 0
	v_mov_b32_dpp v8, v8 quad_perm:[1,0,3,2] row_mask:0xf bank_mask:0xf bound_ctrl:1
	v_fmac_f32_e32 v8, v3, v3
	s_nop 1
	v_add_f32_dpp v8, v8, v8 quad_perm:[2,3,0,1] row_mask:0xf bank_mask:0xf bound_ctrl:1
	s_nop 1
	v_add_f32_dpp v8, v8, v8 row_half_mirror row_mask:0xf bank_mask:0xf bound_ctrl:1
	s_nop 1
	v_add_f32_dpp v8, v8, v8 row_mirror row_mask:0xf bank_mask:0xf bound_ctrl:1
	s_nop 0
	v_readlane_b32 s1, v8, 16
	v_readlane_b32 s6, v8, 48
	v_readlane_b32 s2, v8, 0
	v_readlane_b32 s3, v8, 32
	v_mov_b32_e32 v8, s1
	v_mov_b32_e32 v9, s6
	v_pk_add_f32 v[8:9], s[2:3], v[8:9]
	s_nop 0
	v_add_f32_e32 v8, v8, v9
	v_add_f32_e32 v8, 0x358637bd, v8
	s_nop 0
	v_rsq_f32_e32 v8, v8
	s_nop 0
	v_mul_f32_e32 v3, v3, v8
	v_add_u32_e32 v8, 0x800, v6
	ds_write2_b32 v8, v7, v3 offset0:4 offset1:69
	v_bfe_u32 v7, v3, 16, 1
	v_add3_u32 v3, v3, v7, s15
	v_add_u32_e32 v7, s63, v5
	ds_write_b16_d16_hi v7, v3
	v_pk_mul_f32 v[8:9], v[90:91], v[14:15]
	v_mov_b32_e32 v3, v12
	v_pk_mul_f32 v[2:3], v[92:93], v[2:3]
	v_add_f32_e32 v7, v8, v9
	v_add_f32_e32 v3, v3, v7
	v_add_f32_e32 v2, v2, v3
	v_mul_f32_e32 v3, 0xbfb8aa3b, v2
	v_exp_f32_e32 v3, v3
	v_lshlrev_b32_e32 v12, 16, v102
	v_add_f32_e32 v3, 1.0, v3
	v_rcp_f32_e32 v7, v3
	s_nop 0
	s_nop 0
	v_mul_f32_e32 v7, v2, v7
	v_mul_f32_e32 v2, v7, v7
	v_lshlrev_b32_e32 v8, 16, v97
	v_lshlrev_b32_e32 v9, 16, v100
	v_mov_b32_dpp v2, v2 quad_perm:[1,0,3,2] row_mask:0xf bank_mask:0xf bound_ctrl:1
	v_fmac_f32_e32 v2, v7, v7
	v_lshlrev_b32_e32 v10, 16, v99
	v_lshlrev_b32_e32 v11, 16, v101
	v_add_f32_dpp v2, v2, v2 quad_perm:[2,3,0,1] row_mask:0xf bank_mask:0xf bound_ctrl:1
	s_nop 1
	v_add_f32_dpp v2, v2, v2 row_half_mirror row_mask:0xf bank_mask:0xf bound_ctrl:1
	s_nop 1
	v_add_f32_dpp v2, v2, v2 row_mirror row_mask:0xf bank_mask:0xf bound_ctrl:1
	s_nop 0
	v_readlane_b32 s1, v2, 16
	v_readlane_b32 s6, v2, 48
	v_readlane_b32 s2, v2, 0
	v_readlane_b32 s3, v2, 32
	v_mov_b32_e32 v2, s1
	v_mov_b32_e32 v3, s6
	v_pk_add_f32 v[2:3], s[2:3], v[2:3]
	s_nop 0
	v_add_f32_e32 v2, v2, v3
	v_add_f32_e32 v2, 0x358637bd, v2
	s_nop 0
	v_rsq_f32_e32 v2, v2
	s_nop 0
	v_mul_f32_e32 v2, v7, v2
	v_lshlrev_b32_e32 v7, 16, v98
	s_waitcnt vmcnt(3)
; #define LAS __attribute__((address_space(3)))
; __device__ __forceinline__ float bf2f(bf16 v) { return __uint_as_float(((unsigned)v) << 16); }
; __device__ __forceinline__ unsigned f2bf(float f) { unsigned u = __float_as_uint(f); return (u + 0x7fffu + ((u >> 16) & 1u)) >> 16; }
; __device__ __forceinline__ float sigmoidf_(float x) { return 1.0f / (1.0f + __expf(-x)); }
; __device__ __forceinline__ float siluf_(float x) { return x / (1.0f + __expf(-x)); }
; __device__ __forceinline__ float softplusf_(float x) { return fmaxf(x, 0.f) + __logf(1.0f + __expf(-fabsf(x))); }
; #define AIN(i) ld_ptr(c.la + 2 * (i))
; __device__ __forceinline__ int wy_producer_task(const Ctx& c, int l, int tk, WyPre& P, unsigned* head) {
;     ...
;     for (int j = 0; j < 3; ++j) { float xv[11];
; #pragma unroll
;         for (int r = 0; r < 11; ++r) xv[r] = bf2f((bf16)P.hx[j][r]);
; #pragma unroll
;         for (int r = 0; r < 8; ++r) { const int i = 8 * wid + r;
;             float y = siluf_(P.cw[j][0] * xv[r] + P.cw[j][1] * xv[r + 1] + P.cw[j][2] * xv[r + 2] + P.cw[j][3] * xv[r + 3]);
;             if (j < 2) y *= rsqrtf(wave_sum_fast(y * y) + RMS_EPS) * (j == 0 ? 0.125f : 1.0f);
;             if (j == 0) QF[i * 65 + lane] = y;
;             else if (j == 1) { KF[i * 65 + lane] = y; *(LAS bf16*)(KIMG + (lane >> 3) * 1024 + i * 16 + (lane & 7) * 2) = (bf16)f2bf(y); }
;             else VF[i * 65 + lane] = y; } }
;     if (wid == 0) { const float al = -__expf(((const float*)AIN(I_ALOG))[l * 8 + hh]), dt = ((const float*)AIN(I_DTB))[l * 8 + hh];
;         float g = al * softplusf_(P.sa + dt);
; #pragma unroll
;         for (int o = 1; o < 64; o <<= 1) { const float t = __shfl_up(g, o); if (lane >= o) g += t; }
;         GC[lane] = g; BE[lane] = sigmoidf_(P.sb); }
;     if (wid == 0 && lane == 0) *slot = gnext;
	v_mul_f32_e32 v7, v108, v7
	s_waitcnt vmcnt(2)
	v_fmac_f32_e32 v7, v110, v8
	s_waitcnt vmcnt(1)
	v_fmac_f32_e32 v7, v112, v9
	s_waitcnt vmcnt(0)
	v_fmac_f32_e32 v7, v113, v10
	v_mul_f32_e32 v14, 0xbfb8aa3b, v7
	v_exp_f32_e32 v14, v14
	ds_write_b32 v6, v2 offset:2584
	v_lshlrev_b32_e32 v6, 16, v103
	v_bfe_u32 v3, v2, 16, 1
	v_add_f32_e32 v14, 1.0, v14
	v_rcp_f32_e32 v15, v14
	v_add3_u32 v2, v2, v3, s15
	v_add_u32_e32 v3, s89, v5
	v_lshlrev_b32_e32 v5, 16, v105
	s_nop 0
	v_mul_f32_e32 v7, v7, v15
	v_add_u32_e32 v14, s96, v4
	ds_write_b32 v14, v7
	v_mul_f32_e32 v7, v108, v8
	v_fmac_f32_e32 v7, v110, v9
	v_fmac_f32_e32 v7, v112, v10
	v_fmac_f32_e32 v7, v113, v11
	v_mul_f32_e32 v8, 0xbfb8aa3b, v7
	v_exp_f32_e32 v8, v8
	v_add_u32_e32 v4, s97, v4
	ds_write_b16_d16_hi v3, v2
	v_lshlrev_b32_e32 v3, 16, v106
	v_add_f32_e32 v8, 1.0, v8
	v_rcp_f32_e32 v14, v8
	v_lshlrev_b32_e32 v2, 16, v107
	s_nop 0
	v_mul_f32_e32 v7, v7, v14
	v_mul_f32_e32 v8, v108, v9
	v_fmac_f32_e32 v8, v110, v10
	v_fmac_f32_e32 v8, v112, v11
	v_fmac_f32_e32 v8, v113, v12
	v_mul_f32_e32 v9, 0xbfb8aa3b, v8
	v_exp_f32_e32 v9, v9
	s_nop 0
	v_add_f32_e32 v9, 1.0, v9
	v_rcp_f32_e32 v14, v9
	s_nop 0
	s_nop 0
	v_mul_f32_e32 v8, v8, v14
	ds_write2_b32 v4, v7, v8 offset1:65
	v_mul_f32_e32 v7, v108, v10
	v_fmac_f32_e32 v7, v110, v11
	v_fmac_f32_e32 v7, v112, v12
	v_fmac_f32_e32 v7, v113, v13
	v_mul_f32_e32 v8, 0xbfb8aa3b, v7
	v_exp_f32_e32 v8, v8
	s_nop 0
	v_add_f32_e32 v8, 1.0, v8
	v_rcp_f32_e32 v9, v8
	s_nop 0
	s_nop 0
	v_mul_f32_e32 v7, v7, v9
	v_mul_f32_e32 v8, v108, v11
	v_fmac_f32_e32 v8, v110, v12
	v_fmac_f32_e32 v8, v112, v13
	v_fmac_f32_e32 v8, v113, v6
	v_mul_f32_e32 v9, 0xbfb8aa3b, v8
	v_exp_f32_e32 v9, v9
	s_nop 0
	v_add_f32_e32 v9, 1.0, v9
	v_rcp_f32_e32 v10, v9
	s_nop 0
	s_nop 0
	v_mul_f32_e32 v8, v8, v10
	ds_write2_b32 v4, v7, v8 offset0:130 offset1:195
	v_mul_f32_e32 v7, v108, v12
	v_fmac_f32_e32 v7, v110, v13
	v_fmac_f32_e32 v7, v112, v6
	v_fmac_f32_e32 v7, v113, v5
	v_mul_f32_e32 v8, 0xbfb8aa3b, v7
	v_exp_f32_e32 v8, v8
	s_nop 0
	v_add_f32_e32 v8, 1.0, v8
	v_rcp_f32_e32 v9, v8
	s_nop 0
	s_nop 0
	v_mul_f32_e32 v7, v7, v9
	v_mul_f32_e32 v8, v108, v13
	v_fmac_f32_e32 v8, v110, v6
	v_fmac_f32_e32 v8, v112, v5
	v_fmac_f32_e32 v8, v113, v3
	v_mul_f32_e32 v9, 0xbfb8aa3b, v8
	v_exp_f32_e32 v9, v9
	v_mul_f32_e32 v6, v108, v6
	v_fmac_f32_e32 v6, v110, v5
	v_fmac_f32_e32 v6, v112, v3
	v_add_f32_e32 v9, 1.0, v9
	v_rcp_f32_e32 v10, v9
	v_fmac_f32_e32 v6, v113, v2
	v_mul_f32_e32 v2, 0xbfb8aa3b, v6
	v_exp_f32_e32 v2, v2
	s_nop 0
	v_add_f32_e32 v2, 1.0, v2
	v_div_scale_f32 v3, s[2:3], v2, v2, v6
	v_rcp_f32_e32 v5, v3
	s_nop 0
	v_mul_f32_e32 v8, v8, v10
	v_add_u32_e32 v9, 0x400, v4
	ds_write2_b32 v9, v7, v8 offset0:4 offset1:69
	v_fma_f32 v7, -v3, v5, 1.0
	v_fmac_f32_e32 v5, v7, v5
	v_div_scale_f32 v7, vcc, v6, v2, v6
	v_mul_f32_e32 v8, v7, v5
	v_fma_f32 v9, -v3, v8, v7
	v_fmac_f32_e32 v8, v9, v5
	v_fma_f32 v3, -v3, v8, v7
	v_div_fmas_f32 v3, v3, v5, v8
	v_div_fixup_f32 v2, v3, v2, v6
	s_and_b64 vcc, exec, s[38:39]
	ds_write_b32 v4, v2 offset:1560
	s_cbranch_vccz .LBB0_1093
	s_and_saveexec_b64 s[2:3], s[4:5]

; #define AIN(i) ld_ptr(c.la + 2 * (i))
; __device__ __forceinline__ void wy_prefetch(const Ctx& c, WyPre& P, int l, int tk, int lane, int wid) {
;     const int hh = tk & 7, ch = (tk >> 3) & 63, b = tk >> 9; const size_t row0 = (size_t)b * SEQ + 64 * ch;
;     const bf16* H = (const bf16*)(AWS + WS_H); const float* HS = (const float*)(AWS + WS_HS); const float* cw = (const float*)AIN(I_GCW) + (size_t)l * 4 * GQKV;
; #pragma unroll
;     for (int j = 0; j < 3; ++j) {
; #pragma unroll
;         for (int r = 0; r < 11; ++r) { const int rr = 8 * wid + r - 3;
;             P.hx[j][r] = (ch == 0 && rr < 0) ? (unsigned short)0 : __builtin_nontemporal_load(H + (size_t)((long long)row0 + rr) * HW + HGQKV + j * 512 + hh * 64 + lane); }
; #pragma unroll
;         for (int i = 0; i < 4; ++i) P.cw[j][i] = cw[(size_t)i * GQKV + j * 512 + hh * 64 + lane]; }
;     P.sa = 0.f; P.sb = 0.f;
;     if (wid == 0) { P.sa = HS[(row0 + lane) * 64 + 24 + hh]; P.sb = HS[(row0 + lane) * 64 + 32 + hh]; }
; }
.LBB0_1045:
	ds_read_b32 v20, v1 offset:464
	s_ashr_i32 s2, s12, 9
	s_bfe_u32 s4, s12, 0x60003
	s_ashr_i32 s3, s2, 31
	s_lshl_b64 s[10:11], s[2:3], 12
	s_waitcnt lgkmcnt(0)
	v_readfirstlane_b32 s19, v20
	ds_read_b32 v20, v1 offset:468
	s_lshl_b32 s2, s4, 6
	s_and_b32 s13, s12, 7
	s_or_b32 s10, s10, s2
	s_cmp_eq_u32 s4, 0
	s_waitcnt lgkmcnt(0)
	v_readfirstlane_b32 s22, v20
	ds_read_b32 v20, v1 offset:464
	v_readlane_b32 s4, v255, 12
	s_cselect_b64 s[2:3], -1, 0
	v_readlane_b32 s5, v255, 13
	s_and_b64 s[4:5], s[4:5], s[2:3]
	s_waitcnt lgkmcnt(0)
	v_readfirstlane_b32 s24, v20
	ds_read_b32 v20, v1 offset:468
	s_lshl_b32 s20, s13, 6
	v_ashrrev_i32_e32 v89, 31, v88
	v_mov_b32_e32 v206, 0
	s_and_b64 vcc, exec, s[4:5]
	s_waitcnt lgkmcnt(0)
	v_readfirstlane_b32 s25, v20
	ds_read_b32 v20, v1 offset:360
	v_mov_b32_e32 v207, 0
	s_waitcnt lgkmcnt(0)
	v_readfirstlane_b32 s23, v20
	ds_read_b32 v20, v1 offset:364
	s_waitcnt lgkmcnt(0)
	v_readfirstlane_b32 s26, v20
	s_cbranch_vccnz .LBB0_1047
	s_add_u32 s6, s10, s79
	s_addc_u32 s7, s11, s56
	s_mulk_i32 s7, 0x1c00
	s_mul_hi_u32 s8, s6, 0x1c00
	s_add_i32 s8, s8, s7
	s_mulk_i32 s6, 0x1c00
	s_add_u32 s6, s19, s6
	s_addc_u32 s7, s22, s8
	s_lshl_b32 s8, s20, 1
	s_add_u32 s6, s6, s8
	s_addc_u32 s7, s7, 0
	v_lshl_add_u64 v[20:21], v[88:89], 1, s[6:7]
	v_add_co_u32_e32 v20, vcc, 0xfd00000, v20
	s_nop 1
	v_addc_co_u32_e32 v21, vcc, 0, v21, vcc
	global_load_ushort v207, v[20:21], off offset:2560 nt
.LBB0_1047:
	v_readlane_b32 s6, v255, 14
	v_readlane_b32 s7, v255, 15
	s_and_b64 s[6:7], s[2:3], s[6:7]
	s_and_b64 vcc, exec, s[6:7]
	s_cbranch_vccnz .LBB0_1049
	s_add_u32 s8, s10, s57
	s_addc_u32 s9, s11, s90
	s_mulk_i32 s9, 0x1c00
	s_mul_hi_u32 s16, s8, 0x1c00
	s_add_i32 s16, s16, s9
	s_mulk_i32 s8, 0x1c00
	s_add_u32 s8, s19, s8
	s_addc_u32 s9, s22, s16
	s_lshl_b32 s16, s20, 1
	s_add_u32 s8, s8, s16
	s_addc_u32 s9, s9, 0
	v_lshl_add_u64 v[20:21], v[88:89], 1, s[8:9]
	v_add_co_u32_e32 v20, vcc, 0xfd00000, v20
	s_nop 1
	v_addc_co_u32_e32 v21, vcc, 0, v21, vcc
	global_load_ushort v206, v[20:21], off offset:2560 nt
.LBB0_1049:
	v_readlane_b32 s8, v255, 16
	v_readlane_b32 s9, v255, 17
	s_and_b64 s[16:17], s[2:3], s[8:9]
	v_mov_b32_e32 v208, 0
	s_and_b64 vcc, exec, s[16:17]
	v_mov_b32_e32 v209, 0
	s_cbranch_vccnz .LBB0_1051
	s_add_u32 s8, s10, s54
	s_addc_u32 s9, s11, s55
	s_mulk_i32 s9, 0x1c00
	s_mul_hi_u32 s27, s8, 0x1c00
	s_add_i32 s27, s27, s9
	s_mulk_i32 s8, 0x1c00
	s_add_u32 s8, s19, s8
	s_addc_u32 s9, s22, s27
	s_lshl_b32 s27, s20, 1
	s_add_u32 s8, s8, s27
	s_addc_u32 s9, s9, 0
	v_lshl_add_u64 v[20:21], v[88:89], 1, s[8:9]
	v_add_co_u32_e32 v20, vcc, 0xfd00000, v20
	s_nop 1
	v_addc_co_u32_e32 v21, vcc, 0, v21, vcc
	global_load_ushort v209, v[20:21], off offset:2560 nt
.LBB0_1051:
	s_and_b64 s[2:3], s[72:73], s[2:3]
	s_and_b64 vcc, exec, s[2:3]
	v_lshlrev_b64 v[20:21], 1, v[88:89]
	v_mov_b32_e32 v210, 0
	s_cbranch_vccnz .LBB0_1053
	s_add_u32 s8, s10, s93
	s_addc_u32 s9, s11, s42
	s_mulk_i32 s9, 0x1c00
	s_mul_hi_u32 s27, s8, 0x1c00
	s_add_i32 s27, s27, s9
	s_mulk_i32 s8, 0x1c00
	s_add_u32 s8, s19, s8
	s_addc_u32 s9, s22, s27
	s_lshl_b32 s27, s20, 1
	s_add_u32 s8, s8, s27
	s_addc_u32 s9, s9, 0
	v_lshl_add_u64 v[22:23], s[8:9], 0, v[20:21]
	s_mov_b32 s8, 0xfd00000
	v_add_co_u32_e32 v22, vcc, s8, v22
	s_add_u32 s8, s10, s94
	s_addc_u32 s9, s11, s43
	s_mulk_i32 s9, 0x1c00
	s_mul_hi_u32 s28, s8, 0x1c00
	s_add_i32 s28, s28, s9
	s_mulk_i32 s8, 0x1c00
	s_add_u32 s8, s19, s8
	s_addc_u32 s9, s22, s28
	s_add_u32 s8, s8, s27
	v_addc_co_u32_e32 v23, vcc, 0, v23, vcc
	s_addc_u32 s9, s9, 0
	global_load_ushort v208, v[22:23], off offset:2560 nt
	v_lshl_add_u64 v[22:23], s[8:9], 0, v[20:21]
	v_add_co_u32_e32 v22, vcc, 0xfd00000, v22
	s_nop 1
	v_addc_co_u32_e32 v23, vcc, 0, v23, vcc
	global_load_ushort v210, v[22:23], off offset:2560 nt
.LBB0_1053:
	s_xor_b64 s[8:9], s[2:3], -1
	v_cndmask_b32_e64 v22, 0, 1, s[8:9]
	v_mov_b32_e32 v211, 0
	v_cmp_ne_u32_e64 s[2:3], 1, v22
	s_andn2_b64 vcc, exec, s[8:9]
	v_mov_b32_e32 v212, 0
	v_mov_b32_e32 v213, 0
	s_cbranch_vccnz .LBB0_1055
	s_add_u32 s8, s10, s95
	s_addc_u32 s9, s11, s66
	s_mulk_i32 s9, 0x1c00
	s_mul_hi_u32 s27, s8, 0x1c00
	s_add_i32 s27, s27, s9
	s_mulk_i32 s8, 0x1c00
	s_add_u32 s8, s19, s8
	s_addc_u32 s9, s22, s27
	s_lshl_b32 s27, s20, 1
	s_add_u32 s8, s8, s27
	s_addc_u32 s9, s9, 0
	v_lshl_add_u64 v[22:23], s[8:9], 0, v[20:21]
	s_mov_b32 s8, 0xfd00000
	v_add_co_u32_e32 v22, vcc, s8, v22
	s_add_u32 s8, s10, s50
	s_addc_u32 s9, s11, s67
	s_mulk_i32 s9, 0x1c00
	s_mul_hi_u32 s28, s8, 0x1c00
	s_add_i32 s28, s28, s9
	s_mulk_i32 s8, 0x1c00
	s_add_u32 s8, s19, s8
	s_addc_u32 s9, s22, s28
	s_add_u32 s8, s8, s27
	v_addc_co_u32_e32 v23, vcc, 0, v23, vcc
	s_addc_u32 s9, s9, 0
	global_load_ushort v212, v[22:23], off offset:2560 nt
	v_lshl_add_u64 v[22:23], s[8:9], 0, v[20:21]
	v_add_co_u32_e32 v22, vcc, 0xfd00000, v22
	s_nop 1
	v_addc_co_u32_e32 v23, vcc, 0, v23, vcc
	global_load_ushort v213, v[22:23], off offset:2560 nt
.LBB0_1055:
	s_and_b64 vcc, exec, s[2:3]
	v_mov_b32_e32 v214, 0
	s_cbranch_vccnz .LBB0_1057
	s_add_u32 s8, s10, s51
	s_addc_u32 s9, s11, s48
	s_mulk_i32 s9, 0x1c00
	s_mul_hi_u32 s27, s8, 0x1c00
	s_add_i32 s27, s27, s9
	s_mulk_i32 s8, 0x1c00
	s_add_u32 s8, s19, s8
	s_addc_u32 s9, s22, s27
	s_lshl_b32 s27, s20, 1
	s_add_u32 s8, s8, s27
	s_addc_u32 s9, s9, 0
	v_lshl_add_u64 v[22:23], s[8:9], 0, v[20:21]
	s_mov_b32 s8, 0xfd00000
	v_add_co_u32_e32 v22, vcc, s8, v22
	s_add_u32 s8, s10, s64
	s_addc_u32 s9, s11, s49
	s_mulk_i32 s9, 0x1c00
	s_mul_hi_u32 s28, s8, 0x1c00
	s_add_i32 s28, s28, s9
	s_mulk_i32 s8, 0x1c00
	s_add_u32 s8, s19, s8
	s_addc_u32 s9, s22, s28
	s_add_u32 s8, s8, s27
	v_addc_co_u32_e32 v23, vcc, 0, v23, vcc
	s_addc_u32 s9, s9, 0
	global_load_ushort v211, v[22:23], off offset:2560 nt
	v_lshl_add_u64 v[22:23], s[8:9], 0, v[20:21]
	v_add_co_u32_e32 v22, vcc, 0xfd00000, v22
	s_nop 1
	v_addc_co_u32_e32 v23, vcc, 0, v23, vcc
	global_load_ushort v214, v[22:23], off offset:2560 nt
; #define AIN(i) ld_ptr(c.la + 2 * (i))
; __device__ __forceinline__ void wy_prefetch(const Ctx& c, WyPre& P, int l, int tk, int lane, int wid) {
;     const int hh = tk & 7, ch = (tk >> 3) & 63, b = tk >> 9; const size_t row0 = (size_t)b * SEQ + 64 * ch;
;     const bf16* H = (const bf16*)(AWS + WS_H); const float* HS = (const float*)(AWS + WS_HS); const float* cw = (const float*)AIN(I_GCW) + (size_t)l * 4 * GQKV;
; #pragma unroll
;     for (int j = 0; j < 3; ++j) {
; #pragma unroll
;         for (int r = 0; r < 11; ++r) { const int rr = 8 * wid + r - 3;
;             P.hx[j][r] = (ch == 0 && rr < 0) ? (unsigned short)0 : __builtin_nontemporal_load(H + (size_t)((long long)row0 + rr) * HW + HGQKV + j * 512 + hh * 64 + lane); }
; #pragma unroll
;         for (int i = 0; i < 4; ++i) P.cw[j][i] = cw[(size_t)i * GQKV + j * 512 + hh * 64 + lane]; }
;     P.sa = 0.f; P.sb = 0.f;
;     if (wid == 0) { P.sa = HS[(row0 + lane) * 64 + 24 + hh]; P.sb = HS[(row0 + lane) * 64 + 32 + hh]; }
; }
.LBB0_1057:
	v_mov_b32_e32 v216, 0
	s_and_b64 vcc, exec, s[2:3]
	v_mov_b32_e32 v215, 0
	v_mov_b32_e32 v94, 0
	s_cbranch_vccnz .LBB0_1059
	s_add_u32 s8, s10, s65
	s_addc_u32 s9, s11, s68
	s_mulk_i32 s9, 0x1c00
	s_mul_hi_u32 s27, s8, 0x1c00
	s_add_i32 s27, s27, s9
	s_mulk_i32 s8, 0x1c00
	s_add_u32 s8, s19, s8
	s_addc_u32 s9, s22, s27
	s_lshl_b32 s27, s20, 1
	s_add_u32 s8, s8, s27
	s_addc_u32 s9, s9, 0
	v_lshl_add_u64 v[22:23], s[8:9], 0, v[20:21]
	s_mov_b32 s8, 0xfd00000
	v_add_co_u32_e32 v22, vcc, s8, v22
	s_add_u32 s8, s10, s86
	s_addc_u32 s9, s11, s69
	s_mulk_i32 s9, 0x1c00
	s_mul_hi_u32 s28, s8, 0x1c00
	s_add_i32 s28, s28, s9
	s_mulk_i32 s8, 0x1c00
	s_add_u32 s8, s19, s8
	s_addc_u32 s9, s22, s28
	s_add_u32 s8, s8, s27
	v_addc_co_u32_e32 v23, vcc, 0, v23, vcc
	s_addc_u32 s9, s9, 0
	global_load_ushort v215, v[22:23], off offset:2560 nt
	v_lshl_add_u64 v[22:23], s[8:9], 0, v[20:21]
	v_add_co_u32_e32 v22, vcc, 0xfd00000, v22
	s_nop 1
	v_addc_co_u32_e32 v23, vcc, 0, v23, vcc
	global_load_ushort v94, v[22:23], off offset:2560 nt
.LBB0_1059:
	s_xor_b64 s[8:9], s[4:5], -1
	v_readlane_b32 s4, v254, 62
	v_readlane_b32 s5, v254, 63
	s_add_u32 s4, s23, s4
	s_addc_u32 s5, s26, s5
	s_lshl_b32 s23, s20, 2
	s_add_u32 s4, s4, s23
	s_addc_u32 s5, s5, 0
	v_lshl_add_u64 v[22:23], v[88:89], 2, s[4:5]
	v_add_co_u32_e32 v36, vcc, 0x1000, v22
	global_load_dword v85, v[22:23], off
	s_nop 0
	v_addc_co_u32_e32 v37, vcc, 0, v23, vcc
	global_load_dword v84, v[36:37], off offset:2048
	v_add_co_u32_e32 v36, vcc, 0x3000, v22
	v_cndmask_b32_e64 v35, 0, 1, s[8:9]
	s_nop 0
	v_addc_co_u32_e32 v37, vcc, 0, v23, vcc
	global_load_dword v87, v[36:37], off
	v_add_co_u32_e32 v36, vcc, 0x4000, v22
	v_cmp_ne_u32_e64 s[4:5], 1, v35
	s_nop 0
	v_addc_co_u32_e32 v37, vcc, 0, v23, vcc
	global_load_dword v86, v[36:37], off offset:2048
	s_andn2_b64 vcc, exec, s[8:9]
	s_cbranch_vccnz .LBB0_1061
	s_add_u32 s8, s10, s79
	s_addc_u32 s9, s11, s56
	s_mulk_i32 s9, 0x1c00
	s_mul_hi_u32 s23, s8, 0x1c00
	s_add_i32 s23, s23, s9
	s_mulk_i32 s8, 0x1c00
	s_add_u32 s8, s19, s8
	s_addc_u32 s9, s22, s23
	s_lshl_b32 s23, s20, 1
	s_add_u32 s8, s8, s23
	s_addc_u32 s9, s9, 0
	v_lshl_add_u64 v[36:37], v[88:89], 1, s[8:9]
	v_add_co_u32_e32 v36, vcc, 0xfd00000, v36
	s_nop 1
	v_addc_co_u32_e32 v37, vcc, 0, v37, vcc
	global_load_ushort v216, v[36:37], off offset:3584 nt
.LBB0_1061:
	s_xor_b64 s[8:9], s[6:7], -1
	v_cndmask_b32_e64 v36, 0, 1, s[8:9]
	v_mov_b32_e32 v217, 0
	v_cmp_ne_u32_e64 s[6:7], 1, v36
	s_andn2_b64 vcc, exec, s[8:9]
	v_mov_b32_e32 v218, 0
	s_cbranch_vccnz .LBB0_1063
	s_add_u32 s8, s10, s57
	s_addc_u32 s9, s11, s90
	s_mulk_i32 s9, 0x1c00
	s_mul_hi_u32 s23, s8, 0x1c00
	s_add_i32 s23, s23, s9
	s_mulk_i32 s8, 0x1c00
	s_add_u32 s8, s19, s8
	s_addc_u32 s9, s22, s23
	s_lshl_b32 s23, s20, 1
	s_add_u32 s8, s8, s23
	s_addc_u32 s9, s9, 0
	v_lshl_add_u64 v[36:37], v[88:89], 1, s[8:9]
	v_add_co_u32_e32 v36, vcc, 0xfd00000, v36
	s_nop 1
	v_addc_co_u32_e32 v37, vcc, 0, v37, vcc
	global_load_ushort v218, v[36:37], off offset:3584 nt
.LBB0_1063:
	s_xor_b64 s[8:9], s[16:17], -1
	v_cndmask_b32_e64 v37, 0, 1, s[8:9]
	v_cmp_ne_u32_e64 s[36:37], 1, v37
	s_andn2_b64 vcc, exec, s[8:9]
	s_cbranch_vccnz .LBB0_1065
	s_add_u32 s8, s10, s54
	s_addc_u32 s9, s11, s55
	s_mulk_i32 s9, 0x1c00
	s_mul_hi_u32 s16, s8, 0x1c00
	s_add_i32 s16, s16, s9
	s_mulk_i32 s8, 0x1c00
	s_add_u32 s8, s19, s8
	s_addc_u32 s9, s22, s16
	s_lshl_b32 s16, s20, 1
	s_add_u32 s8, s8, s16
	s_addc_u32 s9, s9, 0
	v_lshl_add_u64 v[38:39], v[88:89], 1, s[8:9]
	v_add_co_u32_e32 v38, vcc, 0xfd00000, v38
	s_nop 1
	v_addc_co_u32_e32 v39, vcc, 0, v39, vcc
	global_load_ushort v217, v[38:39], off offset:3584 nt
; #define AIN(i) ld_ptr(c.la + 2 * (i))
; __device__ __forceinline__ void wy_prefetch(const Ctx& c, WyPre& P, int l, int tk, int lane, int wid) {
;     const int hh = tk & 7, ch = (tk >> 3) & 63, b = tk >> 9; const size_t row0 = (size_t)b * SEQ + 64 * ch;
;     const bf16* H = (const bf16*)(AWS + WS_H); const float* HS = (const float*)(AWS + WS_HS); const float* cw = (const float*)AIN(I_GCW) + (size_t)l * 4 * GQKV;
; #pragma unroll
;     for (int j = 0; j < 3; ++j) {
; #pragma unroll
;         for (int r = 0; r < 11; ++r) { const int rr = 8 * wid + r - 3;
;             P.hx[j][r] = (ch == 0 && rr < 0) ? (unsigned short)0 : __builtin_nontemporal_load(H + (size_t)((long long)row0 + rr) * HW + HGQKV + j * 512 + hh * 64 + lane); }
; #pragma unroll
;         for (int i = 0; i < 4; ++i) P.cw[j][i] = cw[(size_t)i * GQKV + j * 512 + hh * 64 + lane]; }
;     P.sa = 0.f; P.sb = 0.f;
;     if (wid == 0) { P.sa = HS[(row0 + lane) * 64 + 24 + hh]; P.sb = HS[(row0 + lane) * 64 + 32 + hh]; }
; }
.LBB0_1065:
	v_mov_b32_e32 v219, 0
	s_and_b64 vcc, exec, s[2:3]
	v_mov_b32_e32 v230, 0
	v_mov_b32_e32 v231, 0
	s_cbranch_vccnz .LBB0_1067
	s_add_u32 s8, s10, s93
	s_addc_u32 s9, s11, s42
	s_mulk_i32 s9, 0x1c00
	s_mul_hi_u32 s16, s8, 0x1c00
	s_add_i32 s16, s16, s9
	s_mulk_i32 s8, 0x1c00
	s_add_u32 s8, s19, s8
	s_addc_u32 s9, s22, s16
	s_lshl_b32 s16, s20, 1
	s_add_u32 s8, s8, s16
	s_addc_u32 s9, s9, 0
	v_lshl_add_u64 v[38:39], s[8:9], 0, v[20:21]
	s_mov_b32 s8, 0xfd00000
	v_add_co_u32_e32 v38, vcc, s8, v38
	s_add_u32 s8, s10, s94
	s_addc_u32 s9, s11, s43
	s_mulk_i32 s9, 0x1c00
	s_mul_hi_u32 s17, s8, 0x1c00
	s_add_i32 s17, s17, s9
	s_mulk_i32 s8, 0x1c00
	s_add_u32 s8, s19, s8
	s_addc_u32 s9, s22, s17
	s_add_u32 s8, s8, s16
	s_addc_u32 s9, s9, 0
	v_addc_co_u32_e32 v39, vcc, 0, v39, vcc
	v_lshl_add_u64 v[40:41], s[8:9], 0, v[20:21]
	v_add_co_u32_e32 v40, vcc, 0xfd00000, v40
	global_load_ushort v230, v[38:39], off offset:3584 nt
	s_nop 0
	v_addc_co_u32_e32 v41, vcc, 0, v41, vcc
	global_load_ushort v231, v[40:41], off offset:3584 nt
.LBB0_1067:
	s_and_b64 vcc, exec, s[2:3]
	v_mov_b32_e32 v232, 0
	s_cbranch_vccnz .LBB0_1069
	s_add_u32 s8, s10, s95
	s_addc_u32 s9, s11, s66
	s_mulk_i32 s9, 0x1c00
	s_mul_hi_u32 s16, s8, 0x1c00
	s_add_i32 s16, s16, s9
	s_mulk_i32 s8, 0x1c00
	s_add_u32 s8, s19, s8
	s_addc_u32 s9, s22, s16
	s_lshl_b32 s16, s20, 1
	s_add_u32 s8, s8, s16
	s_addc_u32 s9, s9, 0
	v_lshl_add_u64 v[40:41], s[8:9], 0, v[20:21]
	s_mov_b32 s8, 0xfd00000
	v_add_co_u32_e32 v40, vcc, s8, v40
	s_add_u32 s8, s10, s50
	s_addc_u32 s9, s11, s67
	s_mulk_i32 s9, 0x1c00
	s_mul_hi_u32 s17, s8, 0x1c00
	s_add_i32 s17, s17, s9
	s_mulk_i32 s8, 0x1c00
	s_add_u32 s8, s19, s8
	s_addc_u32 s9, s22, s17
	s_add_u32 s8, s8, s16
	v_addc_co_u32_e32 v41, vcc, 0, v41, vcc
	s_addc_u32 s9, s9, 0
	global_load_ushort v219, v[40:41], off offset:3584 nt
	v_lshl_add_u64 v[40:41], s[8:9], 0, v[20:21]
	v_add_co_u32_e32 v40, vcc, 0xfd00000, v40
	s_nop 1
	v_addc_co_u32_e32 v41, vcc, 0, v41, vcc
	global_load_ushort v232, v[40:41], off offset:3584 nt
.LBB0_1069:
	v_mov_b32_e32 v233, 0
	s_and_b64 vcc, exec, s[2:3]
	v_mov_b32_e32 v234, 0
	v_mov_b32_e32 v235, 0
	s_cbranch_vccnz .LBB0_1071
	s_add_u32 s8, s10, s51
	s_addc_u32 s9, s11, s48
	s_mulk_i32 s9, 0x1c00
	s_mul_hi_u32 s16, s8, 0x1c00
	s_add_i32 s16, s16, s9
	s_mulk_i32 s8, 0x1c00
	s_add_u32 s8, s19, s8
	s_addc_u32 s9, s22, s16
	s_lshl_b32 s16, s20, 1
	s_add_u32 s8, s8, s16
	s_addc_u32 s9, s9, 0
	v_lshl_add_u64 v[42:43], s[8:9], 0, v[20:21]
	s_mov_b32 s8, 0xfd00000
	v_add_co_u32_e32 v42, vcc, s8, v42
	s_add_u32 s8, s10, s64
	s_addc_u32 s9, s11, s49
	s_mulk_i32 s9, 0x1c00
	s_mul_hi_u32 s17, s8, 0x1c00
	s_add_i32 s17, s17, s9
	s_mulk_i32 s8, 0x1c00
	s_add_u32 s8, s19, s8
	s_addc_u32 s9, s22, s17
	s_add_u32 s8, s8, s16
	s_addc_u32 s9, s9, 0
	v_addc_co_u32_e32 v43, vcc, 0, v43, vcc
	v_lshl_add_u64 v[44:45], s[8:9], 0, v[20:21]
	v_add_co_u32_e32 v44, vcc, 0xfd00000, v44
	global_load_ushort v234, v[42:43], off offset:3584 nt
	s_nop 0
	v_addc_co_u32_e32 v45, vcc, 0, v45, vcc
	global_load_ushort v235, v[44:45], off offset:3584 nt
.LBB0_1071:
	s_and_b64 vcc, exec, s[2:3]
	v_mov_b32_e32 v96, 0
	s_cbranch_vccnz .LBB0_1073
	s_add_u32 s8, s10, s65
	s_addc_u32 s9, s11, s68
	s_mulk_i32 s9, 0x1c00
	s_mul_hi_u32 s16, s8, 0x1c00
	s_add_i32 s16, s16, s9
	s_mulk_i32 s8, 0x1c00
	s_add_u32 s8, s19, s8
	s_addc_u32 s9, s22, s16
	s_lshl_b32 s16, s20, 1
	s_add_u32 s8, s8, s16
	s_addc_u32 s9, s9, 0
	v_lshl_add_u64 v[44:45], s[8:9], 0, v[20:21]
	s_mov_b32 s8, 0xfd00000
	v_add_co_u32_e32 v44, vcc, s8, v44
	s_add_u32 s8, s10, s86
	s_addc_u32 s9, s11, s69
	s_mulk_i32 s9, 0x1c00
	s_mul_hi_u32 s17, s8, 0x1c00
	s_add_i32 s17, s17, s9
	s_mulk_i32 s8, 0x1c00
	s_add_u32 s8, s19, s8
	s_addc_u32 s9, s22, s17
	s_add_u32 s8, s8, s16
	v_addc_co_u32_e32 v45, vcc, 0, v45, vcc
	s_addc_u32 s9, s9, 0
	global_load_ushort v233, v[44:45], off offset:3584 nt
	v_lshl_add_u64 v[44:45], s[8:9], 0, v[20:21]
	v_add_co_u32_e32 v44, vcc, 0xfd00000, v44
	s_nop 1
	v_addc_co_u32_e32 v45, vcc, 0, v45, vcc
	global_load_ushort v96, v[44:45], off offset:3584 nt

; #define LAS __attribute__((address_space(3)))
; #define WY_RDBLK(m_) do { _Pragma("unroll") for (int t_ = 0; t_ <= (m_); ++t_) LB[(m_) & 1][t_] = *(const LAS f32x4*)(lq + (m_) * WY_BS + 4 * t_); } while (0)
; __device__ __forceinline__ int wy_producer_task(const Ctx& c, int l, int tk, WyPre& P, unsigned* head) {
;     ...
;     {
;         f32x4 LB[2][16];
;         const LAS float* lq = LM + q4 * WY_QS;
;     ...
;         WY_RDBLK(0);
; #pragma unroll
;         for (int m = 0; m < 16; ++m) {
;             if (m + 1 < 16) WY_RDBLK(m + 1);
;             __builtin_amdgcn_sched_barrier(0);
;             f32x4 pre = (f32x4){0.f, 0.f, 0.f, 0.f};
; #pragma unroll
;             for (int t = 0; t < m; ++t) pre = LB[m & 1][t] * own[t] + pre;
; #pragma unroll
;             for (int rr = 0; rr < 4; ++rr) {
;                 float acc = ((q4 == rr) ? own[m] : 0.f) - pre[rr];
;                 if (rr > 0) acc = fmaf(-LB[m & 1][m][rr], own[m], acc);
;                 const float x = quad_sum(acc);
;                 own[m] = (q4 == rr) ? x : own[m]; }
;             __builtin_amdgcn_sched_barrier(0);
;         }
;     ...
;     }
.LBB0_1086:
.LBB0_1087:
	s_movk_i32 s2, 0x110
	v_mad_u32_u24 v21, v0, s2, 0
	s_waitcnt lgkmcnt(0)
	s_barrier
	ds_read_b128 v[22:25], v21 offset:34304
	ds_read_b128 v[26:29], v21 offset:35392
	ds_read_b128 v[30:33], v21 offset:35408
	v_cmp_eq_u32_e64 s[6:7], 0, v0
	v_cmp_eq_u32_e32 vcc, 1, v0
	v_cmp_eq_u32_e64 s[2:3], 2, v0
	v_cndmask_b32_e64 v20, 0, v18, s[6:7]
	s_waitcnt lgkmcnt(2)
	v_cndmask_b32_e32 v22, 0, v18, vcc
	v_cmp_eq_u32_e64 s[4:5], 3, v0
	v_add_f32_dpp v20, v20, v20 quad_perm:[1,0,3,2] row_mask:0xf bank_mask:0xf bound_ctrl:1
	s_nop 1
	v_add_f32_dpp v20, v20, v20 quad_perm:[2,3,0,1] row_mask:0xf bank_mask:0xf bound_ctrl:1
	v_cndmask_b32_e64 v20, v18, v20, s[6:7]
	v_fma_f32 v22, -v23, v20, v22
	s_nop 1
	v_add_f32_dpp v22, v22, v22 quad_perm:[1,0,3,2] row_mask:0xf bank_mask:0xf bound_ctrl:1
	s_nop 1
	v_add_f32_dpp v22, v22, v22 quad_perm:[2,3,0,1] row_mask:0xf bank_mask:0xf bound_ctrl:1
	v_cndmask_b32_e32 v20, v20, v22, vcc
	v_cndmask_b32_e64 v22, 0, v18, s[2:3]
	v_fma_f32 v22, -v24, v20, v22
	v_cndmask_b32_e64 v18, 0, v18, s[4:5]
	s_nop 0
	v_add_f32_dpp v22, v22, v22 quad_perm:[1,0,3,2] row_mask:0xf bank_mask:0xf bound_ctrl:1
	s_nop 1
	v_add_f32_dpp v22, v22, v22 quad_perm:[2,3,0,1] row_mask:0xf bank_mask:0xf bound_ctrl:1
	v_cndmask_b32_e64 v20, v20, v22, s[2:3]
	v_fma_f32 v18, -v25, v20, v18
	s_nop 1
	v_add_f32_dpp v18, v18, v18 quad_perm:[1,0,3,2] row_mask:0xf bank_mask:0xf bound_ctrl:1
	s_nop 1
	v_add_f32_dpp v18, v18, v18 quad_perm:[2,3,0,1] row_mask:0xf bank_mask:0xf bound_ctrl:1
	v_cndmask_b32_e64 v18, v20, v18, s[4:5]
	ds_read_b128 v[22:25], v21 offset:36480
	ds_read_b128 v[34:37], v21 offset:36496
	ds_read_b128 v[38:41], v21 offset:36512
	s_waitcnt lgkmcnt(4)
	v_pk_fma_f32 v[26:27], v[26:27], v[18:19], 0 op_sel_hi:[1,0,0]
	v_cndmask_b32_e64 v20, 0, v19, s[6:7]
	v_sub_f32_e32 v20, v20, v26
	v_cndmask_b32_e32 v26, 0, v19, vcc
	v_sub_f32_e32 v26, v26, v27
	v_add_f32_dpp v20, v20, v20 quad_perm:[1,0,3,2] row_mask:0xf bank_mask:0xf bound_ctrl:1
	v_pk_fma_f32 v[28:29], v[28:29], v[18:19], 0 op_sel_hi:[1,0,0]
	s_nop 0
	v_add_f32_dpp v20, v20, v20 quad_perm:[2,3,0,1] row_mask:0xf bank_mask:0xf bound_ctrl:1
	v_cndmask_b32_e64 v20, v19, v20, s[6:7]
	s_waitcnt lgkmcnt(3)
	v_fma_f32 v26, -v31, v20, v26
	s_nop 1
	v_add_f32_dpp v26, v26, v26 quad_perm:[1,0,3,2] row_mask:0xf bank_mask:0xf bound_ctrl:1
	s_nop 1
	v_add_f32_dpp v26, v26, v26 quad_perm:[2,3,0,1] row_mask:0xf bank_mask:0xf bound_ctrl:1
	v_cndmask_b32_e32 v20, v20, v26, vcc
	v_cndmask_b32_e64 v26, 0, v19, s[2:3]
	v_sub_f32_e32 v26, v26, v28
	v_fma_f32 v26, -v32, v20, v26
	v_cndmask_b32_e64 v19, 0, v19, s[4:5]
	v_sub_f32_e32 v19, v19, v29
	v_add_f32_dpp v26, v26, v26 quad_perm:[1,0,3,2] row_mask:0xf bank_mask:0xf bound_ctrl:1
	s_nop 1
	v_add_f32_dpp v26, v26, v26 quad_perm:[2,3,0,1] row_mask:0xf bank_mask:0xf bound_ctrl:1
	v_cndmask_b32_e64 v20, v20, v26, s[2:3]
	v_fma_f32 v19, -v33, v20, v19
	s_nop 1
	v_add_f32_dpp v19, v19, v19 quad_perm:[1,0,3,2] row_mask:0xf bank_mask:0xf bound_ctrl:1
	s_nop 1
	v_add_f32_dpp v19, v19, v19 quad_perm:[2,3,0,1] row_mask:0xf bank_mask:0xf bound_ctrl:1
	v_cndmask_b32_e64 v20, v20, v19, s[4:5]
	ds_read_b128 v[26:29], v21 offset:37568
	ds_read_b128 v[30:33], v21 offset:37584
	ds_read_b128 v[42:45], v21 offset:37600
	ds_read_b128 v[46:49], v21 offset:37616
	s_waitcnt lgkmcnt(6)
	v_pk_fma_f32 v[22:23], v[22:23], v[18:19], 0 op_sel_hi:[1,0,0]
	v_pk_fma_f32 v[24:25], v[24:25], v[18:19], 0 op_sel_hi:[1,0,0]
	s_waitcnt lgkmcnt(5)
	v_pk_fma_f32 v[22:23], v[34:35], v[20:21], v[22:23] op_sel_hi:[1,0,1]
	v_cndmask_b32_e64 v19, 0, v16, s[6:7]
	v_sub_f32_e32 v19, v19, v22
	v_cndmask_b32_e32 v22, 0, v16, vcc
	v_sub_f32_e32 v22, v22, v23
	v_add_f32_dpp v19, v19, v19 quad_perm:[1,0,3,2] row_mask:0xf bank_mask:0xf bound_ctrl:1
	v_pk_fma_f32 v[24:25], v[36:37], v[20:21], v[24:25] op_sel_hi:[1,0,1]
	s_nop 0
	v_add_f32_dpp v19, v19, v19 quad_perm:[2,3,0,1] row_mask:0xf bank_mask:0xf bound_ctrl:1
	v_cndmask_b32_e64 v19, v16, v19, s[6:7]
	s_waitcnt lgkmcnt(4)
	v_fma_f32 v22, -v39, v19, v22
	s_nop 1
	v_add_f32_dpp v22, v22, v22 quad_perm:[1,0,3,2] row_mask:0xf bank_mask:0xf bound_ctrl:1
	s_nop 1
	v_add_f32_dpp v22, v22, v22 quad_perm:[2,3,0,1] row_mask:0xf bank_mask:0xf bound_ctrl:1
	v_cndmask_b32_e32 v19, v19, v22, vcc
	v_cndmask_b32_e64 v22, 0, v16, s[2:3]
	v_sub_f32_e32 v22, v22, v24
	v_fma_f32 v22, -v40, v19, v22
	v_cndmask_b32_e64 v16, 0, v16, s[4:5]
	v_sub_f32_e32 v16, v16, v25
	v_add_f32_dpp v22, v22, v22 quad_perm:[1,0,3,2] row_mask:0xf bank_mask:0xf bound_ctrl:1
	s_nop 1
	v_add_f32_dpp v22, v22, v22 quad_perm:[2,3,0,1] row_mask:0xf bank_mask:0xf bound_ctrl:1
	v_cndmask_b32_e64 v19, v19, v22, s[2:3]
	v_fma_f32 v16, -v41, v19, v16
	s_nop 1
	v_add_f32_dpp v16, v16, v16 quad_perm:[1,0,3,2] row_mask:0xf bank_mask:0xf bound_ctrl:1
	s_nop 1
	v_add_f32_dpp v16, v16, v16 quad_perm:[2,3,0,1] row_mask:0xf bank_mask:0xf bound_ctrl:1
	v_cndmask_b32_e64 v16, v19, v16, s[4:5]
	ds_read_b128 v[34:37], v21 offset:38656
	ds_read_b128 v[38:41], v21 offset:38672
	ds_read_b128 v[50:53], v21 offset:38688
	ds_read_b128 v[54:57], v21 offset:38704
	ds_read_b128 v[22:25], v21 offset:38720
	s_waitcnt lgkmcnt(8)
	v_pk_fma_f32 v[26:27], v[18:19], v[26:27], 0 op_sel_hi:[0,1,0]
	s_waitcnt lgkmcnt(7)
	v_pk_fma_f32 v[26:27], v[30:31], v[20:21], v[26:27] op_sel_hi:[1,0,1]
	v_pk_fma_f32 v[28:29], v[18:19], v[28:29], 0 op_sel_hi:[0,1,0]
	s_waitcnt lgkmcnt(6)
	v_pk_fma_f32 v[26:27], v[42:43], v[16:17], v[26:27] op_sel_hi:[1,0,1]
	v_cndmask_b32_e64 v19, 0, v17, s[6:7]
	v_sub_f32_e32 v19, v19, v26
	s_waitcnt lgkmcnt(0)
; #define LAS __attribute__((address_space(3)))
; #define WY_RDBLK(m_) do { _Pragma("unroll") for (int t_ = 0; t_ <= (m_); ++t_) LB[(m_) & 1][t_] = *(const LAS f32x4*)(lq + (m_) * WY_BS + 4 * t_); } while (0)
; __device__ __forceinline__ int wy_producer_task(const Ctx& c, int l, int tk, WyPre& P, unsigned* head) {
;     ...
;     {
;         f32x4 LB[2][16];
;         const LAS float* lq = LM + q4 * WY_QS;
;     ...
;         WY_RDBLK(0);
; #pragma unroll
;         for (int m = 0; m < 16; ++m) {
;             if (m + 1 < 16) WY_RDBLK(m + 1);
;             __builtin_amdgcn_sched_barrier(0);
;             f32x4 pre = (f32x4){0.f, 0.f, 0.f, 0.f};
; #pragma unroll
;             for (int t = 0; t < m; ++t) pre = LB[m & 1][t] * own[t] + pre;
; #pragma unroll
;             for (int rr = 0; rr < 4; ++rr) {
;                 float acc = ((q4 == rr) ? own[m] : 0.f) - pre[rr];
;                 if (rr > 0) acc = fmaf(-LB[m & 1][m][rr], own[m], acc);
;                 const float x = quad_sum(acc);
;                 own[m] = (q4 == rr) ? x : own[m]; }
;             __builtin_amdgcn_sched_barrier(0);
;         }
;     ...
;     }
	v_cndmask_b32_e32 v22, 0, v17, vcc
	v_sub_f32_e32 v22, v22, v27
	v_add_f32_dpp v19, v19, v19 quad_perm:[1,0,3,2] row_mask:0xf bank_mask:0xf bound_ctrl:1
	v_pk_fma_f32 v[28:29], v[32:33], v[20:21], v[28:29] op_sel_hi:[1,0,1]
	s_nop 0
	v_add_f32_dpp v19, v19, v19 quad_perm:[2,3,0,1] row_mask:0xf bank_mask:0xf bound_ctrl:1
	v_cndmask_b32_e64 v19, v17, v19, s[6:7]
	v_fma_f32 v22, -v47, v19, v22
	v_pk_fma_f32 v[28:29], v[44:45], v[16:17], v[28:29] op_sel_hi:[1,0,1]
	s_nop 0
	v_add_f32_dpp v22, v22, v22 quad_perm:[1,0,3,2] row_mask:0xf bank_mask:0xf bound_ctrl:1
	s_nop 1
	v_add_f32_dpp v22, v22, v22 quad_perm:[2,3,0,1] row_mask:0xf bank_mask:0xf bound_ctrl:1
	v_cndmask_b32_e32 v19, v19, v22, vcc
	v_cndmask_b32_e64 v22, 0, v17, s[2:3]
	v_sub_f32_e32 v22, v22, v28
	v_fma_f32 v22, -v48, v19, v22
	v_cndmask_b32_e64 v17, 0, v17, s[4:5]
	v_sub_f32_e32 v17, v17, v29
	v_add_f32_dpp v22, v22, v22 quad_perm:[1,0,3,2] row_mask:0xf bank_mask:0xf bound_ctrl:1
	s_nop 1
	v_add_f32_dpp v22, v22, v22 quad_perm:[2,3,0,1] row_mask:0xf bank_mask:0xf bound_ctrl:1
	v_cndmask_b32_e64 v19, v19, v22, s[2:3]
	v_fma_f32 v17, -v49, v19, v17
	s_nop 1
	v_add_f32_dpp v17, v17, v17 quad_perm:[1,0,3,2] row_mask:0xf bank_mask:0xf bound_ctrl:1
	s_nop 1
	v_add_f32_dpp v17, v17, v17 quad_perm:[2,3,0,1] row_mask:0xf bank_mask:0xf bound_ctrl:1
	v_cndmask_b32_e64 v22, v19, v17, s[4:5]
	ds_read_b128 v[26:29], v21 offset:39744
	ds_read_b128 v[30:33], v21 offset:39760
	ds_read_b128 v[42:45], v21 offset:39776
	ds_read_b128 v[46:49], v21 offset:39792
	ds_read_b128 v[58:61], v21 offset:39808
	ds_read_b128 v[62:65], v21 offset:39824
	v_pk_fma_f32 v[34:35], v[18:19], v[34:35], 0 op_sel_hi:[0,1,0]
	v_pk_fma_f32 v[36:37], v[18:19], v[36:37], 0 op_sel_hi:[0,1,0]
	v_pk_fma_f32 v[34:35], v[38:39], v[20:21], v[34:35] op_sel_hi:[1,0,1]
	v_pk_fma_f32 v[36:37], v[40:41], v[20:21], v[36:37] op_sel_hi:[1,0,1]
	v_pk_fma_f32 v[34:35], v[50:51], v[16:17], v[34:35] op_sel_hi:[1,0,1]
	v_pk_fma_f32 v[36:37], v[52:53], v[16:17], v[36:37] op_sel_hi:[1,0,1]
	v_pk_fma_f32 v[34:35], v[54:55], v[22:23], v[34:35] op_sel_hi:[1,0,1]
	v_cndmask_b32_e64 v17, 0, v14, s[6:7]
	v_sub_f32_e32 v17, v17, v34
	v_cndmask_b32_e32 v19, 0, v14, vcc
	v_sub_f32_e32 v19, v19, v35
	v_add_f32_dpp v17, v17, v17 quad_perm:[1,0,3,2] row_mask:0xf bank_mask:0xf bound_ctrl:1
	v_pk_fma_f32 v[36:37], v[56:57], v[22:23], v[36:37] op_sel_hi:[1,0,1]
	s_nop 0
	v_add_f32_dpp v17, v17, v17 quad_perm:[2,3,0,1] row_mask:0xf bank_mask:0xf bound_ctrl:1
	v_cndmask_b32_e64 v17, v14, v17, s[6:7]
	v_fma_f32 v19, -v23, v17, v19
	s_nop 1
	v_add_f32_dpp v19, v19, v19 quad_perm:[1,0,3,2] row_mask:0xf bank_mask:0xf bound_ctrl:1
	s_nop 1
	v_add_f32_dpp v19, v19, v19 quad_perm:[2,3,0,1] row_mask:0xf bank_mask:0xf bound_ctrl:1
	v_cndmask_b32_e32 v17, v17, v19, vcc
	v_cndmask_b32_e64 v19, 0, v14, s[2:3]
	v_sub_f32_e32 v19, v19, v36
	v_fma_f32 v19, -v24, v17, v19
	v_cndmask_b32_e64 v14, 0, v14, s[4:5]
	v_sub_f32_e32 v14, v14, v37
	v_add_f32_dpp v19, v19, v19 quad_perm:[1,0,3,2] row_mask:0xf bank_mask:0xf bound_ctrl:1
	s_nop 1
	v_add_f32_dpp v19, v19, v19 quad_perm:[2,3,0,1] row_mask:0xf bank_mask:0xf bound_ctrl:1
	v_cndmask_b32_e64 v17, v17, v19, s[2:3]
	v_fma_f32 v14, -v25, v17, v14
	s_nop 1
	v_add_f32_dpp v14, v14, v14 quad_perm:[1,0,3,2] row_mask:0xf bank_mask:0xf bound_ctrl:1
	s_nop 1
	v_add_f32_dpp v14, v14, v14 quad_perm:[2,3,0,1] row_mask:0xf bank_mask:0xf bound_ctrl:1
	v_cndmask_b32_e64 v14, v17, v14, s[4:5]
	ds_read_b128 v[34:37], v21 offset:40832
	ds_read_b128 v[38:41], v21 offset:40848
	ds_read_b128 v[50:53], v21 offset:40864
	ds_read_b128 v[54:57], v21 offset:40880
	ds_read_b128 v[66:69], v21 offset:40896
	ds_read_b128 v[70:73], v21 offset:40912
	ds_read_b128 v[74:77], v21 offset:40928
	s_waitcnt lgkmcnt(12)
	v_pk_fma_f32 v[26:27], v[18:19], v[26:27], 0 op_sel_hi:[0,1,0]
	s_waitcnt lgkmcnt(11)
	v_pk_fma_f32 v[26:27], v[20:21], v[30:31], v[26:27] op_sel_hi:[0,1,1]
	v_pk_fma_f32 v[24:25], v[18:19], v[28:29], 0 op_sel_hi:[0,1,0]
	s_waitcnt lgkmcnt(10)
	v_pk_fma_f32 v[26:27], v[42:43], v[16:17], v[26:27] op_sel_hi:[1,0,1]
	v_pk_fma_f32 v[24:25], v[20:21], v[32:33], v[24:25] op_sel_hi:[0,1,1]
	s_waitcnt lgkmcnt(9)
	v_pk_fma_f32 v[26:27], v[46:47], v[22:23], v[26:27] op_sel_hi:[1,0,1]
	v_pk_fma_f32 v[24:25], v[44:45], v[16:17], v[24:25] op_sel_hi:[1,0,1]
	s_waitcnt lgkmcnt(8)
	v_pk_fma_f32 v[26:27], v[58:59], v[14:15], v[26:27] op_sel_hi:[1,0,1]
	v_cndmask_b32_e64 v17, 0, v15, s[6:7]
	v_sub_f32_e32 v17, v17, v26
	v_cndmask_b32_e32 v19, 0, v15, vcc
	v_sub_f32_e32 v19, v19, v27
	v_add_f32_dpp v17, v17, v17 quad_perm:[1,0,3,2] row_mask:0xf bank_mask:0xf bound_ctrl:1
	v_pk_fma_f32 v[24:25], v[48:49], v[22:23], v[24:25] op_sel_hi:[1,0,1]
	s_nop 0
	v_add_f32_dpp v17, v17, v17 quad_perm:[2,3,0,1] row_mask:0xf bank_mask:0xf bound_ctrl:1
	v_cndmask_b32_e64 v17, v15, v17, s[6:7]
	s_waitcnt lgkmcnt(7)
	v_fma_f32 v19, -v63, v17, v19
	v_pk_fma_f32 v[24:25], v[60:61], v[14:15], v[24:25] op_sel_hi:[1,0,1]
	s_nop 0
	v_add_f32_dpp v19, v19, v19 quad_perm:[1,0,3,2] row_mask:0xf bank_mask:0xf bound_ctrl:1
	s_nop 1
	v_add_f32_dpp v19, v19, v19 quad_perm:[2,3,0,1] row_mask:0xf bank_mask:0xf bound_ctrl:1
	v_cndmask_b32_e32 v17, v17, v19, vcc
	v_cndmask_b32_e64 v19, 0, v15, s[2:3]
	v_sub_f32_e32 v19, v19, v24
	v_fma_f32 v19, -v64, v17, v19
	v_cndmask_b32_e64 v15, 0, v15, s[4:5]
	v_sub_f32_e32 v15, v15, v25
	v_add_f32_dpp v19, v19, v19 quad_perm:[1,0,3,2] row_mask:0xf bank_mask:0xf bound_ctrl:1
	s_nop 1
	v_add_f32_dpp v19, v19, v19 quad_perm:[2,3,0,1] row_mask:0xf bank_mask:0xf bound_ctrl:1
	v_cndmask_b32_e64 v17, v17, v19, s[2:3]
	v_fma_f32 v15, -v65, v17, v15
	s_nop 1
	v_add_f32_dpp v15, v15, v15 quad_perm:[1,0,3,2] row_mask:0xf bank_mask:0xf bound_ctrl:1
	s_nop 1
	v_add_f32_dpp v15, v15, v15 quad_perm:[2,3,0,1] row_mask:0xf bank_mask:0xf bound_ctrl:1
	v_cndmask_b32_e64 v24, v17, v15, s[4:5]
	ds_read_b128 v[26:29], v21 offset:41920
	ds_read_b128 v[30:33], v21 offset:41936
	ds_read_b128 v[42:45], v21 offset:41952
	ds_read_b128 v[46:49], v21 offset:41968
	ds_read_b128 v[58:61], v21 offset:41984
	ds_read_b128 v[62:65], v21 offset:42000
	ds_read_b128 v[78:81], v21 offset:42016
	ds_read_b128 v[126:129], v21 offset:42032
	s_waitcnt lgkmcnt(14)
; #define LAS __attribute__((address_space(3)))
; #define WY_RDBLK(m_) do { _Pragma("unroll") for (int t_ = 0; t_ <= (m_); ++t_) LB[(m_) & 1][t_] = *(const LAS f32x4*)(lq + (m_) * WY_BS + 4 * t_); } while (0)
; __device__ __forceinline__ int wy_producer_task(const Ctx& c, int l, int tk, WyPre& P, unsigned* head) {
;     ...
;     {
;         f32x4 LB[2][16];
;         const LAS float* lq = LM + q4 * WY_QS;
;     ...
;         WY_RDBLK(0);
; #pragma unroll
;         for (int m = 0; m < 16; ++m) {
;             if (m + 1 < 16) WY_RDBLK(m + 1);
;             __builtin_amdgcn_sched_barrier(0);
;             f32x4 pre = (f32x4){0.f, 0.f, 0.f, 0.f};
; #pragma unroll
;             for (int t = 0; t < m; ++t) pre = LB[m & 1][t] * own[t] + pre;
; #pragma unroll
;             for (int rr = 0; rr < 4; ++rr) {
;                 float acc = ((q4 == rr) ? own[m] : 0.f) - pre[rr];
;                 if (rr > 0) acc = fmaf(-LB[m & 1][m][rr], own[m], acc);
;                 const float x = quad_sum(acc);
;                 own[m] = (q4 == rr) ? x : own[m]; }
;             __builtin_amdgcn_sched_barrier(0);
;         }
;     ...
;     }
	v_pk_fma_f32 v[34:35], v[18:19], v[34:35], 0 op_sel_hi:[0,1,0]
	v_pk_fma_f32 v[36:37], v[18:19], v[36:37], 0 op_sel_hi:[0,1,0]
	s_waitcnt lgkmcnt(13)
	v_pk_fma_f32 v[34:35], v[20:21], v[38:39], v[34:35] op_sel_hi:[0,1,1]
	v_pk_fma_f32 v[36:37], v[20:21], v[40:41], v[36:37] op_sel_hi:[0,1,1]
	s_waitcnt lgkmcnt(12)
	v_pk_fma_f32 v[34:35], v[16:17], v[50:51], v[34:35] op_sel_hi:[0,1,1]
	v_pk_fma_f32 v[36:37], v[16:17], v[52:53], v[36:37] op_sel_hi:[0,1,1]
	s_waitcnt lgkmcnt(11)
	v_pk_fma_f32 v[34:35], v[54:55], v[22:23], v[34:35] op_sel_hi:[1,0,1]
	v_pk_fma_f32 v[36:37], v[56:57], v[22:23], v[36:37] op_sel_hi:[1,0,1]
	s_waitcnt lgkmcnt(10)
	v_pk_fma_f32 v[34:35], v[66:67], v[14:15], v[34:35] op_sel_hi:[1,0,1]
	v_pk_fma_f32 v[36:37], v[68:69], v[14:15], v[36:37] op_sel_hi:[1,0,1]
	s_waitcnt lgkmcnt(9)
	v_pk_fma_f32 v[34:35], v[70:71], v[24:25], v[34:35] op_sel_hi:[1,0,1]
	v_cndmask_b32_e64 v15, 0, v12, s[6:7]
	v_sub_f32_e32 v15, v15, v34
	v_cndmask_b32_e32 v17, 0, v12, vcc
	v_sub_f32_e32 v17, v17, v35
	v_add_f32_dpp v15, v15, v15 quad_perm:[1,0,3,2] row_mask:0xf bank_mask:0xf bound_ctrl:1
	v_pk_fma_f32 v[36:37], v[72:73], v[24:25], v[36:37] op_sel_hi:[1,0,1]
	s_nop 0
	v_add_f32_dpp v15, v15, v15 quad_perm:[2,3,0,1] row_mask:0xf bank_mask:0xf bound_ctrl:1
	v_cndmask_b32_e64 v15, v12, v15, s[6:7]
	s_waitcnt lgkmcnt(8)
	v_fma_f32 v17, -v75, v15, v17
	s_nop 1
	v_add_f32_dpp v17, v17, v17 quad_perm:[1,0,3,2] row_mask:0xf bank_mask:0xf bound_ctrl:1
	s_nop 1
	v_add_f32_dpp v17, v17, v17 quad_perm:[2,3,0,1] row_mask:0xf bank_mask:0xf bound_ctrl:1
	v_cndmask_b32_e32 v15, v15, v17, vcc
	v_cndmask_b32_e64 v17, 0, v12, s[2:3]
	v_sub_f32_e32 v17, v17, v36
	v_fma_f32 v17, -v76, v15, v17
	v_cndmask_b32_e64 v12, 0, v12, s[4:5]
	v_sub_f32_e32 v12, v12, v37
	v_add_f32_dpp v17, v17, v17 quad_perm:[1,0,3,2] row_mask:0xf bank_mask:0xf bound_ctrl:1
	s_nop 1
	v_add_f32_dpp v17, v17, v17 quad_perm:[2,3,0,1] row_mask:0xf bank_mask:0xf bound_ctrl:1
	v_cndmask_b32_e64 v15, v15, v17, s[2:3]
	v_fma_f32 v12, -v77, v15, v12
	s_nop 1
	v_add_f32_dpp v12, v12, v12 quad_perm:[1,0,3,2] row_mask:0xf bank_mask:0xf bound_ctrl:1
	s_nop 1
	v_add_f32_dpp v12, v12, v12 quad_perm:[2,3,0,1] row_mask:0xf bank_mask:0xf bound_ctrl:1
	v_cndmask_b32_e64 v12, v15, v12, s[4:5]
	ds_read_b128 v[34:37], v21 offset:43008
	ds_read_b128 v[38:41], v21 offset:43024
	ds_read_b128 v[50:53], v21 offset:43040
	ds_read_b128 v[54:57], v21 offset:43056
	ds_read_b128 v[66:69], v21 offset:43072
	ds_read_b128 v[70:73], v21 offset:43088
	ds_read_b128 v[74:77], v21 offset:43104
	ds_read_b128 v[130:133], v21 offset:43120
	ds_read_b128 v[134:137], v21 offset:43136
	s_waitcnt lgkmcnt(14)
	v_pk_fma_f32 v[26:27], v[18:19], v[26:27], 0 op_sel_hi:[0,1,0]
	v_pk_fma_f32 v[26:27], v[20:21], v[30:31], v[26:27] op_sel_hi:[0,1,1]
	v_pk_fma_f32 v[28:29], v[18:19], v[28:29], 0 op_sel_hi:[0,1,0]
	v_pk_fma_f32 v[26:27], v[16:17], v[42:43], v[26:27] op_sel_hi:[0,1,1]
	v_pk_fma_f32 v[28:29], v[20:21], v[32:33], v[28:29] op_sel_hi:[0,1,1]
	s_waitcnt lgkmcnt(13)
	v_pk_fma_f32 v[26:27], v[22:23], v[46:47], v[26:27] op_sel_hi:[0,1,1]
	v_pk_fma_f32 v[28:29], v[16:17], v[44:45], v[28:29] op_sel_hi:[0,1,1]
	s_waitcnt lgkmcnt(12)
	v_pk_fma_f32 v[26:27], v[58:59], v[14:15], v[26:27] op_sel_hi:[1,0,1]
	v_pk_fma_f32 v[28:29], v[22:23], v[48:49], v[28:29] op_sel_hi:[0,1,1]
	s_waitcnt lgkmcnt(11)
	v_pk_fma_f32 v[26:27], v[62:63], v[24:25], v[26:27] op_sel_hi:[1,0,1]
	v_pk_fma_f32 v[28:29], v[60:61], v[14:15], v[28:29] op_sel_hi:[1,0,1]
	s_waitcnt lgkmcnt(10)
	v_pk_fma_f32 v[26:27], v[78:79], v[12:13], v[26:27] op_sel_hi:[1,0,1]
	v_cndmask_b32_e64 v15, 0, v13, s[6:7]
	v_sub_f32_e32 v15, v15, v26
	v_cndmask_b32_e32 v17, 0, v13, vcc
	v_sub_f32_e32 v17, v17, v27
	v_add_f32_dpp v15, v15, v15 quad_perm:[1,0,3,2] row_mask:0xf bank_mask:0xf bound_ctrl:1
	v_pk_fma_f32 v[28:29], v[64:65], v[24:25], v[28:29] op_sel_hi:[1,0,1]
	s_nop 0
	v_add_f32_dpp v15, v15, v15 quad_perm:[2,3,0,1] row_mask:0xf bank_mask:0xf bound_ctrl:1
	v_cndmask_b32_e64 v15, v13, v15, s[6:7]
	s_waitcnt lgkmcnt(9)
	v_fma_f32 v17, -v127, v15, v17
	v_pk_fma_f32 v[28:29], v[80:81], v[12:13], v[28:29] op_sel_hi:[1,0,1]
	s_nop 0
	v_add_f32_dpp v17, v17, v17 quad_perm:[1,0,3,2] row_mask:0xf bank_mask:0xf bound_ctrl:1
	s_nop 1
	v_add_f32_dpp v17, v17, v17 quad_perm:[2,3,0,1] row_mask:0xf bank_mask:0xf bound_ctrl:1
	v_cndmask_b32_e32 v15, v15, v17, vcc
	v_cndmask_b32_e64 v17, 0, v13, s[2:3]
	v_sub_f32_e32 v17, v17, v28
	v_fma_f32 v17, -v128, v15, v17
	v_cndmask_b32_e64 v13, 0, v13, s[4:5]
	v_sub_f32_e32 v13, v13, v29
	v_add_f32_dpp v17, v17, v17 quad_perm:[1,0,3,2] row_mask:0xf bank_mask:0xf bound_ctrl:1
	s_nop 1
	v_add_f32_dpp v17, v17, v17 quad_perm:[2,3,0,1] row_mask:0xf bank_mask:0xf bound_ctrl:1
	v_cndmask_b32_e64 v15, v15, v17, s[2:3]
	v_fma_f32 v13, -v129, v15, v13
	s_nop 1
	v_add_f32_dpp v13, v13, v13 quad_perm:[1,0,3,2] row_mask:0xf bank_mask:0xf bound_ctrl:1
	s_nop 1
	v_add_f32_dpp v13, v13, v13 quad_perm:[2,3,0,1] row_mask:0xf bank_mask:0xf bound_ctrl:1
	v_cndmask_b32_e64 v26, v15, v13, s[4:5]
	ds_read_b128 v[28:31], v21 offset:44096
	ds_read_b128 v[42:45], v21 offset:44112
	ds_read_b128 v[46:49], v21 offset:44128
	ds_read_b128 v[58:61], v21 offset:44144
	ds_read_b128 v[62:65], v21 offset:44160
	ds_read_b128 v[78:81], v21 offset:44176
	ds_read_b128 v[126:129], v21 offset:44192
	ds_read_b128 v[138:141], v21 offset:44208
	ds_read_b128 v[142:145], v21 offset:44224
	ds_read_b128 v[146:149], v21 offset:44240
	s_waitcnt lgkmcnt(14)
; #define LAS __attribute__((address_space(3)))
; #define WY_RDBLK(m_) do { _Pragma("unroll") for (int t_ = 0; t_ <= (m_); ++t_) LB[(m_) & 1][t_] = *(const LAS f32x4*)(lq + (m_) * WY_BS + 4 * t_); } while (0)
; __device__ __forceinline__ int wy_producer_task(const Ctx& c, int l, int tk, WyPre& P, unsigned* head) {
;     ...
;     {
;         f32x4 LB[2][16];
;         const LAS float* lq = LM + q4 * WY_QS;
;     ...
;         WY_RDBLK(0);
; #pragma unroll
;         for (int m = 0; m < 16; ++m) {
;             if (m + 1 < 16) WY_RDBLK(m + 1);
;             __builtin_amdgcn_sched_barrier(0);
;             f32x4 pre = (f32x4){0.f, 0.f, 0.f, 0.f};
; #pragma unroll
;             for (int t = 0; t < m; ++t) pre = LB[m & 1][t] * own[t] + pre;
; #pragma unroll
;             for (int rr = 0; rr < 4; ++rr) {
;                 float acc = ((q4 == rr) ? own[m] : 0.f) - pre[rr];
;                 if (rr > 0) acc = fmaf(-LB[m & 1][m][rr], own[m], acc);
;                 const float x = quad_sum(acc);
;                 own[m] = (q4 == rr) ? x : own[m]; }
;             __builtin_amdgcn_sched_barrier(0);
;         }
;     ...
;     }
	v_pk_fma_f32 v[32:33], v[18:19], v[34:35], 0 op_sel_hi:[0,1,0]
	v_pk_fma_f32 v[34:35], v[18:19], v[36:37], 0 op_sel_hi:[0,1,0]
	v_pk_fma_f32 v[32:33], v[20:21], v[38:39], v[32:33] op_sel_hi:[0,1,1]
	v_pk_fma_f32 v[34:35], v[20:21], v[40:41], v[34:35] op_sel_hi:[0,1,1]
	v_pk_fma_f32 v[32:33], v[16:17], v[50:51], v[32:33] op_sel_hi:[0,1,1]
	v_pk_fma_f32 v[34:35], v[16:17], v[52:53], v[34:35] op_sel_hi:[0,1,1]
	v_pk_fma_f32 v[32:33], v[22:23], v[54:55], v[32:33] op_sel_hi:[0,1,1]
	v_pk_fma_f32 v[34:35], v[22:23], v[56:57], v[34:35] op_sel_hi:[0,1,1]
	v_pk_fma_f32 v[32:33], v[14:15], v[66:67], v[32:33] op_sel_hi:[0,1,1]
	v_pk_fma_f32 v[34:35], v[14:15], v[68:69], v[34:35] op_sel_hi:[0,1,1]
	s_waitcnt lgkmcnt(13)
	v_pk_fma_f32 v[32:33], v[70:71], v[24:25], v[32:33] op_sel_hi:[1,0,1]
	v_pk_fma_f32 v[34:35], v[72:73], v[24:25], v[34:35] op_sel_hi:[1,0,1]
	s_waitcnt lgkmcnt(12)
	v_pk_fma_f32 v[32:33], v[74:75], v[12:13], v[32:33] op_sel_hi:[1,0,1]
	v_pk_fma_f32 v[34:35], v[76:77], v[12:13], v[34:35] op_sel_hi:[1,0,1]
	s_waitcnt lgkmcnt(11)
	v_pk_fma_f32 v[32:33], v[130:131], v[26:27], v[32:33] op_sel_hi:[1,0,1]
	v_cndmask_b32_e64 v13, 0, v10, s[6:7]
	v_sub_f32_e32 v13, v13, v32
	v_cndmask_b32_e32 v15, 0, v10, vcc
	v_sub_f32_e32 v15, v15, v33
	v_add_f32_dpp v13, v13, v13 quad_perm:[1,0,3,2] row_mask:0xf bank_mask:0xf bound_ctrl:1
	v_pk_fma_f32 v[34:35], v[132:133], v[26:27], v[34:35] op_sel_hi:[1,0,1]
	s_nop 0
	v_add_f32_dpp v13, v13, v13 quad_perm:[2,3,0,1] row_mask:0xf bank_mask:0xf bound_ctrl:1
	v_cndmask_b32_e64 v13, v10, v13, s[6:7]
	s_waitcnt lgkmcnt(10)
	v_fma_f32 v15, -v135, v13, v15
	s_nop 1
	v_add_f32_dpp v15, v15, v15 quad_perm:[1,0,3,2] row_mask:0xf bank_mask:0xf bound_ctrl:1
	s_nop 1
	v_add_f32_dpp v15, v15, v15 quad_perm:[2,3,0,1] row_mask:0xf bank_mask:0xf bound_ctrl:1
	v_cndmask_b32_e32 v13, v13, v15, vcc
	v_cndmask_b32_e64 v15, 0, v10, s[2:3]
	v_sub_f32_e32 v15, v15, v34
	v_fma_f32 v15, -v136, v13, v15
	v_cndmask_b32_e64 v10, 0, v10, s[4:5]
	v_sub_f32_e32 v10, v10, v35
	v_add_f32_dpp v15, v15, v15 quad_perm:[1,0,3,2] row_mask:0xf bank_mask:0xf bound_ctrl:1
	s_nop 1
	v_add_f32_dpp v15, v15, v15 quad_perm:[2,3,0,1] row_mask:0xf bank_mask:0xf bound_ctrl:1
	v_cndmask_b32_e64 v13, v13, v15, s[2:3]
	v_fma_f32 v10, -v137, v13, v10
	s_nop 1
	v_add_f32_dpp v10, v10, v10 quad_perm:[1,0,3,2] row_mask:0xf bank_mask:0xf bound_ctrl:1
	s_nop 1
	v_add_f32_dpp v10, v10, v10 quad_perm:[2,3,0,1] row_mask:0xf bank_mask:0xf bound_ctrl:1
	v_cndmask_b32_e64 v10, v13, v10, s[4:5]
	ds_read_b128 v[32:35], v21 offset:45184
	ds_read_b128 v[36:39], v21 offset:45200
	ds_read_b128 v[50:53], v21 offset:45216
	ds_read_b128 v[54:57], v21 offset:45232
	ds_read_b128 v[66:69], v21 offset:45248
	ds_read_b128 v[70:73], v21 offset:45264
	ds_read_b128 v[74:77], v21 offset:45280
	ds_read_b128 v[130:133], v21 offset:45296
	ds_read_b128 v[134:137], v21 offset:45312
	ds_read_b128 v[150:153], v21 offset:45328
	ds_read_b128 v[154:157], v21 offset:45344
	s_waitcnt lgkmcnt(14)
	v_pk_fma_f32 v[28:29], v[18:19], v[28:29], 0 op_sel_hi:[0,1,0]
	v_pk_fma_f32 v[28:29], v[20:21], v[42:43], v[28:29] op_sel_hi:[0,1,1]
	v_pk_fma_f32 v[30:31], v[18:19], v[30:31], 0 op_sel_hi:[0,1,0]
	v_pk_fma_f32 v[28:29], v[16:17], v[46:47], v[28:29] op_sel_hi:[0,1,1]
	v_pk_fma_f32 v[30:31], v[20:21], v[44:45], v[30:31] op_sel_hi:[0,1,1]
	v_pk_fma_f32 v[28:29], v[22:23], v[58:59], v[28:29] op_sel_hi:[0,1,1]
	v_pk_fma_f32 v[30:31], v[16:17], v[48:49], v[30:31] op_sel_hi:[0,1,1]
	v_pk_fma_f32 v[28:29], v[14:15], v[62:63], v[28:29] op_sel_hi:[0,1,1]
	v_pk_fma_f32 v[30:31], v[22:23], v[60:61], v[30:31] op_sel_hi:[0,1,1]
	v_pk_fma_f32 v[28:29], v[24:25], v[78:79], v[28:29] op_sel_hi:[0,1,1]
	v_pk_fma_f32 v[30:31], v[14:15], v[64:65], v[30:31] op_sel_hi:[0,1,1]
	v_pk_fma_f32 v[28:29], v[126:127], v[12:13], v[28:29] op_sel_hi:[1,0,1]
	v_pk_fma_f32 v[30:31], v[24:25], v[80:81], v[30:31] op_sel_hi:[0,1,1]
	s_waitcnt lgkmcnt(13)
	v_pk_fma_f32 v[28:29], v[138:139], v[26:27], v[28:29] op_sel_hi:[1,0,1]
	v_pk_fma_f32 v[30:31], v[128:129], v[12:13], v[30:31] op_sel_hi:[1,0,1]
	s_waitcnt lgkmcnt(12)
	v_pk_fma_f32 v[28:29], v[142:143], v[10:11], v[28:29] op_sel_hi:[1,0,1]
	v_cndmask_b32_e64 v13, 0, v11, s[6:7]
	v_sub_f32_e32 v13, v13, v28
	v_cndmask_b32_e32 v15, 0, v11, vcc
	v_sub_f32_e32 v15, v15, v29
	v_add_f32_dpp v13, v13, v13 quad_perm:[1,0,3,2] row_mask:0xf bank_mask:0xf bound_ctrl:1
	v_pk_fma_f32 v[30:31], v[140:141], v[26:27], v[30:31] op_sel_hi:[1,0,1]
	s_nop 0
	v_add_f32_dpp v13, v13, v13 quad_perm:[2,3,0,1] row_mask:0xf bank_mask:0xf bound_ctrl:1
	v_cndmask_b32_e64 v13, v11, v13, s[6:7]
	s_waitcnt lgkmcnt(11)
	v_fma_f32 v15, -v147, v13, v15
	v_pk_fma_f32 v[30:31], v[144:145], v[10:11], v[30:31] op_sel_hi:[1,0,1]
	s_nop 0
	v_add_f32_dpp v15, v15, v15 quad_perm:[1,0,3,2] row_mask:0xf bank_mask:0xf bound_ctrl:1
	s_nop 1
	v_add_f32_dpp v15, v15, v15 quad_perm:[2,3,0,1] row_mask:0xf bank_mask:0xf bound_ctrl:1
	v_cndmask_b32_e32 v13, v13, v15, vcc
	v_cndmask_b32_e64 v15, 0, v11, s[2:3]
	v_sub_f32_e32 v15, v15, v30
	v_fma_f32 v15, -v148, v13, v15
	v_cndmask_b32_e64 v11, 0, v11, s[4:5]
	v_sub_f32_e32 v11, v11, v31
	v_add_f32_dpp v15, v15, v15 quad_perm:[1,0,3,2] row_mask:0xf bank_mask:0xf bound_ctrl:1
	s_nop 1
	v_add_f32_dpp v15, v15, v15 quad_perm:[2,3,0,1] row_mask:0xf bank_mask:0xf bound_ctrl:1
	v_cndmask_b32_e64 v13, v13, v15, s[2:3]
	v_fma_f32 v11, -v149, v13, v11
	s_nop 1
	v_add_f32_dpp v11, v11, v11 quad_perm:[1,0,3,2] row_mask:0xf bank_mask:0xf bound_ctrl:1
	s_nop 1
	v_add_f32_dpp v11, v11, v11 quad_perm:[2,3,0,1] row_mask:0xf bank_mask:0xf bound_ctrl:1
	v_cndmask_b32_e64 v28, v13, v11, s[4:5]
	ds_read_b128 v[40:43], v21 offset:46272
	ds_read_b128 v[44:47], v21 offset:46288
	ds_read_b128 v[58:61], v21 offset:46304
	ds_read_b128 v[62:65], v21 offset:46320
	ds_read_b128 v[78:81], v21 offset:46336
	ds_read_b128 v[126:129], v21 offset:46352
	ds_read_b128 v[138:141], v21 offset:46368
	ds_read_b128 v[142:145], v21 offset:46384
	ds_read_b128 v[146:149], v21 offset:46400
	ds_read_b128 v[158:161], v21 offset:46416
	ds_read_b128 v[162:165], v21 offset:46432
	ds_read_b128 v[166:169], v21 offset:46448
	s_waitcnt lgkmcnt(14)
; #define LAS __attribute__((address_space(3)))
; #define WY_RDBLK(m_) do { _Pragma("unroll") for (int t_ = 0; t_ <= (m_); ++t_) LB[(m_) & 1][t_] = *(const LAS f32x4*)(lq + (m_) * WY_BS + 4 * t_); } while (0)
; __device__ __forceinline__ int wy_producer_task(const Ctx& c, int l, int tk, WyPre& P, unsigned* head) {
;     ...
;     {
;         f32x4 LB[2][16];
;         const LAS float* lq = LM + q4 * WY_QS;
;     ...
;         WY_RDBLK(0);
; #pragma unroll
;         for (int m = 0; m < 16; ++m) {
;             if (m + 1 < 16) WY_RDBLK(m + 1);
;             __builtin_amdgcn_sched_barrier(0);
;             f32x4 pre = (f32x4){0.f, 0.f, 0.f, 0.f};
; #pragma unroll
;             for (int t = 0; t < m; ++t) pre = LB[m & 1][t] * own[t] + pre;
; #pragma unroll
;             for (int rr = 0; rr < 4; ++rr) {
;                 float acc = ((q4 == rr) ? own[m] : 0.f) - pre[rr];
;                 if (rr > 0) acc = fmaf(-LB[m & 1][m][rr], own[m], acc);
;                 const float x = quad_sum(acc);
;                 own[m] = (q4 == rr) ? x : own[m]; }
;             __builtin_amdgcn_sched_barrier(0);
;         }
;     ...
;     }
	v_pk_fma_f32 v[30:31], v[18:19], v[32:33], 0 op_sel_hi:[0,1,0]
	v_pk_fma_f32 v[32:33], v[18:19], v[34:35], 0 op_sel_hi:[0,1,0]
	v_pk_fma_f32 v[30:31], v[20:21], v[36:37], v[30:31] op_sel_hi:[0,1,1]
	v_pk_fma_f32 v[32:33], v[20:21], v[38:39], v[32:33] op_sel_hi:[0,1,1]
	v_pk_fma_f32 v[30:31], v[16:17], v[50:51], v[30:31] op_sel_hi:[0,1,1]
	v_pk_fma_f32 v[32:33], v[16:17], v[52:53], v[32:33] op_sel_hi:[0,1,1]
	v_pk_fma_f32 v[30:31], v[22:23], v[54:55], v[30:31] op_sel_hi:[0,1,1]
	v_pk_fma_f32 v[32:33], v[22:23], v[56:57], v[32:33] op_sel_hi:[0,1,1]
	v_pk_fma_f32 v[30:31], v[14:15], v[66:67], v[30:31] op_sel_hi:[0,1,1]
	v_pk_fma_f32 v[32:33], v[14:15], v[68:69], v[32:33] op_sel_hi:[0,1,1]
	v_pk_fma_f32 v[30:31], v[24:25], v[70:71], v[30:31] op_sel_hi:[0,1,1]
	v_pk_fma_f32 v[32:33], v[24:25], v[72:73], v[32:33] op_sel_hi:[0,1,1]
	v_pk_fma_f32 v[30:31], v[12:13], v[74:75], v[30:31] op_sel_hi:[0,1,1]
	v_pk_fma_f32 v[32:33], v[12:13], v[76:77], v[32:33] op_sel_hi:[0,1,1]
	v_pk_fma_f32 v[30:31], v[130:131], v[26:27], v[30:31] op_sel_hi:[1,0,1]
	v_pk_fma_f32 v[32:33], v[132:133], v[26:27], v[32:33] op_sel_hi:[1,0,1]
	v_pk_fma_f32 v[30:31], v[134:135], v[10:11], v[30:31] op_sel_hi:[1,0,1]
	v_pk_fma_f32 v[32:33], v[136:137], v[10:11], v[32:33] op_sel_hi:[1,0,1]
	s_waitcnt lgkmcnt(13)
	v_pk_fma_f32 v[30:31], v[150:151], v[28:29], v[30:31] op_sel_hi:[1,0,1]
	v_cndmask_b32_e64 v11, 0, v8, s[6:7]
	v_sub_f32_e32 v11, v11, v30
	v_cndmask_b32_e32 v13, 0, v8, vcc
	v_sub_f32_e32 v13, v13, v31
	v_add_f32_dpp v11, v11, v11 quad_perm:[1,0,3,2] row_mask:0xf bank_mask:0xf bound_ctrl:1
	v_pk_fma_f32 v[32:33], v[152:153], v[28:29], v[32:33] op_sel_hi:[1,0,1]
	s_nop 0
	v_add_f32_dpp v11, v11, v11 quad_perm:[2,3,0,1] row_mask:0xf bank_mask:0xf bound_ctrl:1
	v_cndmask_b32_e64 v11, v8, v11, s[6:7]
	s_waitcnt lgkmcnt(12)
	v_fma_f32 v13, -v155, v11, v13
	s_nop 1
	v_add_f32_dpp v13, v13, v13 quad_perm:[1,0,3,2] row_mask:0xf bank_mask:0xf bound_ctrl:1
	s_nop 1
	v_add_f32_dpp v13, v13, v13 quad_perm:[2,3,0,1] row_mask:0xf bank_mask:0xf bound_ctrl:1
	v_cndmask_b32_e32 v11, v11, v13, vcc
	v_cndmask_b32_e64 v13, 0, v8, s[2:3]
	v_sub_f32_e32 v13, v13, v32
	v_fma_f32 v13, -v156, v11, v13
	v_cndmask_b32_e64 v8, 0, v8, s[4:5]
	v_sub_f32_e32 v8, v8, v33
	v_add_f32_dpp v13, v13, v13 quad_perm:[1,0,3,2] row_mask:0xf bank_mask:0xf bound_ctrl:1
	s_nop 1
	v_add_f32_dpp v13, v13, v13 quad_perm:[2,3,0,1] row_mask:0xf bank_mask:0xf bound_ctrl:1
	v_cndmask_b32_e64 v11, v11, v13, s[2:3]
	v_fma_f32 v8, -v157, v11, v8
	s_nop 1
	v_add_f32_dpp v8, v8, v8 quad_perm:[1,0,3,2] row_mask:0xf bank_mask:0xf bound_ctrl:1
	s_nop 1
	v_add_f32_dpp v8, v8, v8 quad_perm:[2,3,0,1] row_mask:0xf bank_mask:0xf bound_ctrl:1
	v_cndmask_b32_e64 v8, v11, v8, s[4:5]
	ds_read_b128 v[32:35], v21 offset:47360
	ds_read_b128 v[36:39], v21 offset:47376
	ds_read_b128 v[48:51], v21 offset:47392
	ds_read_b128 v[52:55], v21 offset:47408
	ds_read_b128 v[66:69], v21 offset:47424
	ds_read_b128 v[70:73], v21 offset:47440
	ds_read_b128 v[74:77], v21 offset:47456
	ds_read_b128 v[130:133], v21 offset:47472
	ds_read_b128 v[134:137], v21 offset:47488
	ds_read_b128 v[150:153], v21 offset:47504
	ds_read_b128 v[154:157], v21 offset:47520
	ds_read_b128 v[170:173], v21 offset:47536
	ds_read_b128 v[174:177], v21 offset:47552
	s_waitcnt lgkmcnt(14)
	v_pk_fma_f32 v[40:41], v[18:19], v[40:41], 0 op_sel_hi:[0,1,0]
	v_pk_fma_f32 v[40:41], v[20:21], v[44:45], v[40:41] op_sel_hi:[0,1,1]
	v_pk_fma_f32 v[30:31], v[18:19], v[42:43], 0 op_sel_hi:[0,1,0]
	v_pk_fma_f32 v[40:41], v[16:17], v[58:59], v[40:41] op_sel_hi:[0,1,1]
	v_pk_fma_f32 v[30:31], v[20:21], v[46:47], v[30:31] op_sel_hi:[0,1,1]
	v_pk_fma_f32 v[40:41], v[22:23], v[62:63], v[40:41] op_sel_hi:[0,1,1]
	v_pk_fma_f32 v[30:31], v[16:17], v[60:61], v[30:31] op_sel_hi:[0,1,1]
	v_pk_fma_f32 v[40:41], v[14:15], v[78:79], v[40:41] op_sel_hi:[0,1,1]
	v_pk_fma_f32 v[30:31], v[22:23], v[64:65], v[30:31] op_sel_hi:[0,1,1]
	v_pk_fma_f32 v[40:41], v[24:25], v[126:127], v[40:41] op_sel_hi:[0,1,1]
	v_pk_fma_f32 v[30:31], v[14:15], v[80:81], v[30:31] op_sel_hi:[0,1,1]
	v_pk_fma_f32 v[40:41], v[12:13], v[138:139], v[40:41] op_sel_hi:[0,1,1]
	v_pk_fma_f32 v[30:31], v[24:25], v[128:129], v[30:31] op_sel_hi:[0,1,1]
	v_pk_fma_f32 v[40:41], v[26:27], v[142:143], v[40:41] op_sel_hi:[0,1,1]
	v_pk_fma_f32 v[30:31], v[12:13], v[140:141], v[30:31] op_sel_hi:[0,1,1]
	v_pk_fma_f32 v[40:41], v[146:147], v[10:11], v[40:41] op_sel_hi:[1,0,1]
	v_pk_fma_f32 v[30:31], v[26:27], v[144:145], v[30:31] op_sel_hi:[0,1,1]
	v_pk_fma_f32 v[40:41], v[158:159], v[28:29], v[40:41] op_sel_hi:[1,0,1]
	v_pk_fma_f32 v[30:31], v[148:149], v[10:11], v[30:31] op_sel_hi:[1,0,1]
	v_pk_fma_f32 v[40:41], v[162:163], v[8:9], v[40:41] op_sel_hi:[1,0,1]
	v_cndmask_b32_e64 v11, 0, v9, s[6:7]
	v_sub_f32_e32 v11, v11, v40
	v_cndmask_b32_e32 v13, 0, v9, vcc
	v_sub_f32_e32 v13, v13, v41
	v_add_f32_dpp v11, v11, v11 quad_perm:[1,0,3,2] row_mask:0xf bank_mask:0xf bound_ctrl:1
	v_pk_fma_f32 v[30:31], v[160:161], v[28:29], v[30:31] op_sel_hi:[1,0,1]
	s_nop 0
	v_add_f32_dpp v11, v11, v11 quad_perm:[2,3,0,1] row_mask:0xf bank_mask:0xf bound_ctrl:1
	v_cndmask_b32_e64 v11, v9, v11, s[6:7]
	s_waitcnt lgkmcnt(13)
; #define LAS __attribute__((address_space(3)))
; #define WY_RDBLK(m_) do { _Pragma("unroll") for (int t_ = 0; t_ <= (m_); ++t_) LB[(m_) & 1][t_] = *(const LAS f32x4*)(lq + (m_) * WY_BS + 4 * t_); } while (0)
; __device__ __forceinline__ int wy_producer_task(const Ctx& c, int l, int tk, WyPre& P, unsigned* head) {
;     ...
;     {
;         f32x4 LB[2][16];
;         const LAS float* lq = LM + q4 * WY_QS;
;     ...
;         WY_RDBLK(0);
; #pragma unroll
;         for (int m = 0; m < 16; ++m) {
;             if (m + 1 < 16) WY_RDBLK(m + 1);
;             __builtin_amdgcn_sched_barrier(0);
;             f32x4 pre = (f32x4){0.f, 0.f, 0.f, 0.f};
; #pragma unroll
;             for (int t = 0; t < m; ++t) pre = LB[m & 1][t] * own[t] + pre;
; #pragma unroll
;             for (int rr = 0; rr < 4; ++rr) {
;                 float acc = ((q4 == rr) ? own[m] : 0.f) - pre[rr];
;                 if (rr > 0) acc = fmaf(-LB[m & 1][m][rr], own[m], acc);
;                 const float x = quad_sum(acc);
;                 own[m] = (q4 == rr) ? x : own[m]; }
;             __builtin_amdgcn_sched_barrier(0);
;         }
;     ...
;     }
	v_fma_f32 v13, -v167, v11, v13
	v_pk_fma_f32 v[30:31], v[164:165], v[8:9], v[30:31] op_sel_hi:[1,0,1]
	s_nop 0
	v_add_f32_dpp v13, v13, v13 quad_perm:[1,0,3,2] row_mask:0xf bank_mask:0xf bound_ctrl:1
	s_nop 1
	v_add_f32_dpp v13, v13, v13 quad_perm:[2,3,0,1] row_mask:0xf bank_mask:0xf bound_ctrl:1
	v_cndmask_b32_e32 v11, v11, v13, vcc
	v_cndmask_b32_e64 v13, 0, v9, s[2:3]
	v_sub_f32_e32 v13, v13, v30
	v_fma_f32 v13, -v168, v11, v13
	v_cndmask_b32_e64 v9, 0, v9, s[4:5]
	v_sub_f32_e32 v9, v9, v31
	v_add_f32_dpp v13, v13, v13 quad_perm:[1,0,3,2] row_mask:0xf bank_mask:0xf bound_ctrl:1
	s_nop 1
	v_add_f32_dpp v13, v13, v13 quad_perm:[2,3,0,1] row_mask:0xf bank_mask:0xf bound_ctrl:1
	v_cndmask_b32_e64 v11, v11, v13, s[2:3]
	v_fma_f32 v9, -v169, v11, v9
	s_nop 1
	v_add_f32_dpp v9, v9, v9 quad_perm:[1,0,3,2] row_mask:0xf bank_mask:0xf bound_ctrl:1
	s_nop 1
	v_add_f32_dpp v9, v9, v9 quad_perm:[2,3,0,1] row_mask:0xf bank_mask:0xf bound_ctrl:1
	v_cndmask_b32_e64 v30, v11, v9, s[4:5]
	ds_read_b128 v[40:43], v21 offset:48448
	ds_read_b128 v[44:47], v21 offset:48464
	ds_read_b128 v[56:59], v21 offset:48480
	ds_read_b128 v[60:63], v21 offset:48496
	ds_read_b128 v[78:81], v21 offset:48512
	ds_read_b128 v[126:129], v21 offset:48528
	ds_read_b128 v[138:141], v21 offset:48544
	ds_read_b128 v[142:145], v21 offset:48560
	ds_read_b128 v[146:149], v21 offset:48576
	ds_read_b128 v[158:161], v21 offset:48592
	ds_read_b128 v[162:165], v21 offset:48608
	ds_read_b128 v[166:169], v21 offset:48624
	ds_read_b128 v[178:181], v21 offset:48640
	ds_read_b128 v[182:185], v21 offset:48656
	s_waitcnt lgkmcnt(14)
	v_pk_fma_f32 v[32:33], v[18:19], v[32:33], 0 op_sel_hi:[0,1,0]
	v_pk_fma_f32 v[34:35], v[18:19], v[34:35], 0 op_sel_hi:[0,1,0]
	v_pk_fma_f32 v[32:33], v[20:21], v[36:37], v[32:33] op_sel_hi:[0,1,1]
	v_pk_fma_f32 v[34:35], v[20:21], v[38:39], v[34:35] op_sel_hi:[0,1,1]
	v_pk_fma_f32 v[32:33], v[16:17], v[48:49], v[32:33] op_sel_hi:[0,1,1]
	v_pk_fma_f32 v[34:35], v[16:17], v[50:51], v[34:35] op_sel_hi:[0,1,1]
	v_pk_fma_f32 v[32:33], v[22:23], v[52:53], v[32:33] op_sel_hi:[0,1,1]
	v_pk_fma_f32 v[34:35], v[22:23], v[54:55], v[34:35] op_sel_hi:[0,1,1]
	v_pk_fma_f32 v[32:33], v[14:15], v[66:67], v[32:33] op_sel_hi:[0,1,1]
	v_pk_fma_f32 v[34:35], v[14:15], v[68:69], v[34:35] op_sel_hi:[0,1,1]
	v_pk_fma_f32 v[32:33], v[24:25], v[70:71], v[32:33] op_sel_hi:[0,1,1]
	v_pk_fma_f32 v[34:35], v[24:25], v[72:73], v[34:35] op_sel_hi:[0,1,1]
	v_pk_fma_f32 v[32:33], v[12:13], v[74:75], v[32:33] op_sel_hi:[0,1,1]
	v_pk_fma_f32 v[34:35], v[12:13], v[76:77], v[34:35] op_sel_hi:[0,1,1]
	v_pk_fma_f32 v[32:33], v[26:27], v[130:131], v[32:33] op_sel_hi:[0,1,1]
	v_pk_fma_f32 v[34:35], v[26:27], v[132:133], v[34:35] op_sel_hi:[0,1,1]
	v_pk_fma_f32 v[32:33], v[10:11], v[134:135], v[32:33] op_sel_hi:[0,1,1]
	v_pk_fma_f32 v[34:35], v[10:11], v[136:137], v[34:35] op_sel_hi:[0,1,1]
	v_pk_fma_f32 v[32:33], v[150:151], v[28:29], v[32:33] op_sel_hi:[1,0,1]
	v_pk_fma_f32 v[34:35], v[152:153], v[28:29], v[34:35] op_sel_hi:[1,0,1]
	v_pk_fma_f32 v[32:33], v[154:155], v[8:9], v[32:33] op_sel_hi:[1,0,1]
	v_pk_fma_f32 v[34:35], v[156:157], v[8:9], v[34:35] op_sel_hi:[1,0,1]
	v_pk_fma_f32 v[32:33], v[170:171], v[30:31], v[32:33] op_sel_hi:[1,0,1]
	v_cndmask_b32_e64 v9, 0, v6, s[6:7]
	v_sub_f32_e32 v9, v9, v32
	v_cndmask_b32_e32 v11, 0, v6, vcc
	v_sub_f32_e32 v11, v11, v33
	v_add_f32_dpp v9, v9, v9 quad_perm:[1,0,3,2] row_mask:0xf bank_mask:0xf bound_ctrl:1
	v_pk_fma_f32 v[34:35], v[172:173], v[30:31], v[34:35] op_sel_hi:[1,0,1]
	s_nop 0
	v_add_f32_dpp v9, v9, v9 quad_perm:[2,3,0,1] row_mask:0xf bank_mask:0xf bound_ctrl:1
	v_cndmask_b32_e64 v9, v6, v9, s[6:7]
	v_fma_f32 v11, -v175, v9, v11
	s_nop 1
	v_add_f32_dpp v11, v11, v11 quad_perm:[1,0,3,2] row_mask:0xf bank_mask:0xf bound_ctrl:1
	s_nop 1
	v_add_f32_dpp v11, v11, v11 quad_perm:[2,3,0,1] row_mask:0xf bank_mask:0xf bound_ctrl:1
	v_cndmask_b32_e32 v9, v9, v11, vcc
	v_cndmask_b32_e64 v11, 0, v6, s[2:3]
	v_sub_f32_e32 v11, v11, v34
	v_fma_f32 v11, -v176, v9, v11
	v_cndmask_b32_e64 v6, 0, v6, s[4:5]
	v_sub_f32_e32 v6, v6, v35
	v_add_f32_dpp v11, v11, v11 quad_perm:[1,0,3,2] row_mask:0xf bank_mask:0xf bound_ctrl:1
	s_nop 1
	v_add_f32_dpp v11, v11, v11 quad_perm:[2,3,0,1] row_mask:0xf bank_mask:0xf bound_ctrl:1
	v_cndmask_b32_e64 v9, v9, v11, s[2:3]
	v_fma_f32 v6, -v177, v9, v6
	s_nop 1
	v_add_f32_dpp v6, v6, v6 quad_perm:[1,0,3,2] row_mask:0xf bank_mask:0xf bound_ctrl:1
	s_nop 1
	v_add_f32_dpp v6, v6, v6 quad_perm:[2,3,0,1] row_mask:0xf bank_mask:0xf bound_ctrl:1
	v_cndmask_b32_e64 v6, v9, v6, s[4:5]
	ds_read_b128 v[34:37], v21 offset:49536
	ds_read_b128 v[48:51], v21 offset:49552
	ds_read_b128 v[52:55], v21 offset:49568
	ds_read_b128 v[64:67], v21 offset:49584
	ds_read_b128 v[68:71], v21 offset:49600
	ds_read_b128 v[72:75], v21 offset:49616
	ds_read_b128 v[130:133], v21 offset:49632
	ds_read_b128 v[134:137], v21 offset:49648
	ds_read_b128 v[150:153], v21 offset:49664
	ds_read_b128 v[154:157], v21 offset:49680
	ds_read_b128 v[170:173], v21 offset:49696
	ds_read_b128 v[174:177], v21 offset:49712
	ds_read_b128 v[186:189], v21 offset:49728
	ds_read_b128 v[190:193], v21 offset:49744
	ds_read_b128 v[194:197], v21 offset:49760
	s_waitcnt lgkmcnt(14)
; #define LAS __attribute__((address_space(3)))
; #define WY_RDBLK(m_) do { _Pragma("unroll") for (int t_ = 0; t_ <= (m_); ++t_) LB[(m_) & 1][t_] = *(const LAS f32x4*)(lq + (m_) * WY_BS + 4 * t_); } while (0)
; __device__ __forceinline__ int wy_producer_task(const Ctx& c, int l, int tk, WyPre& P, unsigned* head) {
;     ...
;     {
;         f32x4 LB[2][16];
;         const LAS float* lq = LM + q4 * WY_QS;
;     ...
;         WY_RDBLK(0);
; #pragma unroll
;         for (int m = 0; m < 16; ++m) {
;             if (m + 1 < 16) WY_RDBLK(m + 1);
;             __builtin_amdgcn_sched_barrier(0);
;             f32x4 pre = (f32x4){0.f, 0.f, 0.f, 0.f};
; #pragma unroll
;             for (int t = 0; t < m; ++t) pre = LB[m & 1][t] * own[t] + pre;
; #pragma unroll
;             for (int rr = 0; rr < 4; ++rr) {
;                 float acc = ((q4 == rr) ? own[m] : 0.f) - pre[rr];
;                 if (rr > 0) acc = fmaf(-LB[m & 1][m][rr], own[m], acc);
;                 const float x = quad_sum(acc);
;                 own[m] = (q4 == rr) ? x : own[m]; }
;             __builtin_amdgcn_sched_barrier(0);
;         }
;     ...
;     }
	v_pk_fma_f32 v[38:39], v[18:19], v[40:41], 0 op_sel_hi:[0,1,0]
	v_pk_fma_f32 v[38:39], v[20:21], v[44:45], v[38:39] op_sel_hi:[0,1,1]
	v_pk_fma_f32 v[32:33], v[18:19], v[42:43], 0 op_sel_hi:[0,1,0]
	v_pk_fma_f32 v[38:39], v[16:17], v[56:57], v[38:39] op_sel_hi:[0,1,1]
	v_pk_fma_f32 v[32:33], v[20:21], v[46:47], v[32:33] op_sel_hi:[0,1,1]
	v_pk_fma_f32 v[38:39], v[22:23], v[60:61], v[38:39] op_sel_hi:[0,1,1]
	v_pk_fma_f32 v[32:33], v[16:17], v[58:59], v[32:33] op_sel_hi:[0,1,1]
	v_pk_fma_f32 v[38:39], v[14:15], v[78:79], v[38:39] op_sel_hi:[0,1,1]
	v_pk_fma_f32 v[32:33], v[22:23], v[62:63], v[32:33] op_sel_hi:[0,1,1]
	v_pk_fma_f32 v[38:39], v[24:25], v[126:127], v[38:39] op_sel_hi:[0,1,1]
	v_pk_fma_f32 v[32:33], v[14:15], v[80:81], v[32:33] op_sel_hi:[0,1,1]
	v_pk_fma_f32 v[38:39], v[12:13], v[138:139], v[38:39] op_sel_hi:[0,1,1]
	v_pk_fma_f32 v[32:33], v[24:25], v[128:129], v[32:33] op_sel_hi:[0,1,1]
	v_pk_fma_f32 v[38:39], v[26:27], v[142:143], v[38:39] op_sel_hi:[0,1,1]
	v_pk_fma_f32 v[32:33], v[12:13], v[140:141], v[32:33] op_sel_hi:[0,1,1]
	v_pk_fma_f32 v[38:39], v[10:11], v[146:147], v[38:39] op_sel_hi:[0,1,1]
	v_pk_fma_f32 v[32:33], v[26:27], v[144:145], v[32:33] op_sel_hi:[0,1,1]
	v_pk_fma_f32 v[38:39], v[28:29], v[158:159], v[38:39] op_sel_hi:[0,1,1]
	v_pk_fma_f32 v[32:33], v[10:11], v[148:149], v[32:33] op_sel_hi:[0,1,1]
	v_pk_fma_f32 v[38:39], v[162:163], v[8:9], v[38:39] op_sel_hi:[1,0,1]
	v_pk_fma_f32 v[32:33], v[28:29], v[160:161], v[32:33] op_sel_hi:[0,1,1]
	v_pk_fma_f32 v[38:39], v[166:167], v[30:31], v[38:39] op_sel_hi:[1,0,1]
	v_pk_fma_f32 v[32:33], v[164:165], v[8:9], v[32:33] op_sel_hi:[1,0,1]
	v_pk_fma_f32 v[38:39], v[178:179], v[6:7], v[38:39] op_sel_hi:[1,0,1]
	v_cndmask_b32_e64 v9, 0, v7, s[6:7]
	v_sub_f32_e32 v9, v9, v38
	v_cndmask_b32_e32 v11, 0, v7, vcc
	v_sub_f32_e32 v11, v11, v39
	v_add_f32_dpp v9, v9, v9 quad_perm:[1,0,3,2] row_mask:0xf bank_mask:0xf bound_ctrl:1
	v_pk_fma_f32 v[32:33], v[168:169], v[30:31], v[32:33] op_sel_hi:[1,0,1]
	s_nop 0
	v_add_f32_dpp v9, v9, v9 quad_perm:[2,3,0,1] row_mask:0xf bank_mask:0xf bound_ctrl:1
	v_cndmask_b32_e64 v9, v7, v9, s[6:7]
	v_fma_f32 v11, -v183, v9, v11
	v_pk_fma_f32 v[32:33], v[180:181], v[6:7], v[32:33] op_sel_hi:[1,0,1]
	s_nop 0
	v_add_f32_dpp v11, v11, v11 quad_perm:[1,0,3,2] row_mask:0xf bank_mask:0xf bound_ctrl:1
	s_nop 1
	v_add_f32_dpp v11, v11, v11 quad_perm:[2,3,0,1] row_mask:0xf bank_mask:0xf bound_ctrl:1
	v_cndmask_b32_e32 v9, v9, v11, vcc
	v_cndmask_b32_e64 v11, 0, v7, s[2:3]
	v_sub_f32_e32 v11, v11, v32
	v_fma_f32 v11, -v184, v9, v11
	v_cndmask_b32_e64 v7, 0, v7, s[4:5]
	v_sub_f32_e32 v7, v7, v33
	v_add_f32_dpp v11, v11, v11 quad_perm:[1,0,3,2] row_mask:0xf bank_mask:0xf bound_ctrl:1
	s_nop 1
	v_add_f32_dpp v11, v11, v11 quad_perm:[2,3,0,1] row_mask:0xf bank_mask:0xf bound_ctrl:1
	v_cndmask_b32_e64 v9, v9, v11, s[2:3]
	v_fma_f32 v7, -v185, v9, v7
	s_nop 1
	v_add_f32_dpp v7, v7, v7 quad_perm:[1,0,3,2] row_mask:0xf bank_mask:0xf bound_ctrl:1
	s_nop 1
	v_add_f32_dpp v7, v7, v7 quad_perm:[2,3,0,1] row_mask:0xf bank_mask:0xf bound_ctrl:1
	v_cndmask_b32_e64 v32, v9, v7, s[4:5]
	ds_read_b128 v[38:41], v21 offset:50624
	ds_read_b128 v[42:45], v21 offset:50640
	ds_read_b128 v[56:59], v21 offset:50656
	ds_read_b128 v[60:63], v21 offset:50672
	ds_read_b128 v[76:79], v21 offset:50688
	ds_read_b128 v[126:129], v21 offset:50704
	ds_read_b128 v[138:141], v21 offset:50720
	ds_read_b128 v[142:145], v21 offset:50736
	ds_read_b128 v[146:149], v21 offset:50752
	ds_read_b128 v[158:161], v21 offset:50768
	ds_read_b128 v[162:165], v21 offset:50784
	ds_read_b128 v[166:169], v21 offset:50800
	ds_read_b128 v[178:181], v21 offset:50816
	ds_read_b128 v[182:185], v21 offset:50832
	ds_read_b128 v[198:201], v21 offset:50848
	ds_read_b128 v[202:205], v21 offset:50864
	v_pk_fma_f32 v[34:35], v[18:19], v[34:35], 0 op_sel_hi:[0,1,0]
	v_pk_fma_f32 v[36:37], v[18:19], v[36:37], 0 op_sel_hi:[0,1,0]
	s_waitcnt lgkmcnt(14)
	v_pk_fma_f32 v[34:35], v[20:21], v[48:49], v[34:35] op_sel_hi:[0,1,1]
	v_pk_fma_f32 v[36:37], v[20:21], v[50:51], v[36:37] op_sel_hi:[0,1,1]
	v_pk_fma_f32 v[34:35], v[16:17], v[52:53], v[34:35] op_sel_hi:[0,1,1]
	v_pk_fma_f32 v[36:37], v[16:17], v[54:55], v[36:37] op_sel_hi:[0,1,1]
	v_pk_fma_f32 v[34:35], v[22:23], v[64:65], v[34:35] op_sel_hi:[0,1,1]
	v_pk_fma_f32 v[36:37], v[22:23], v[66:67], v[36:37] op_sel_hi:[0,1,1]
	v_pk_fma_f32 v[34:35], v[14:15], v[68:69], v[34:35] op_sel_hi:[0,1,1]
	v_pk_fma_f32 v[36:37], v[14:15], v[70:71], v[36:37] op_sel_hi:[0,1,1]
	v_pk_fma_f32 v[34:35], v[24:25], v[72:73], v[34:35] op_sel_hi:[0,1,1]
	v_pk_fma_f32 v[36:37], v[24:25], v[74:75], v[36:37] op_sel_hi:[0,1,1]
	v_pk_fma_f32 v[34:35], v[12:13], v[130:131], v[34:35] op_sel_hi:[0,1,1]
	v_pk_fma_f32 v[36:37], v[12:13], v[132:133], v[36:37] op_sel_hi:[0,1,1]
	v_pk_fma_f32 v[34:35], v[26:27], v[134:135], v[34:35] op_sel_hi:[0,1,1]
	v_pk_fma_f32 v[36:37], v[26:27], v[136:137], v[36:37] op_sel_hi:[0,1,1]
	v_pk_fma_f32 v[34:35], v[10:11], v[150:151], v[34:35] op_sel_hi:[0,1,1]
	v_pk_fma_f32 v[36:37], v[10:11], v[152:153], v[36:37] op_sel_hi:[0,1,1]
	v_pk_fma_f32 v[34:35], v[28:29], v[154:155], v[34:35] op_sel_hi:[0,1,1]
	v_pk_fma_f32 v[36:37], v[28:29], v[156:157], v[36:37] op_sel_hi:[0,1,1]
	v_pk_fma_f32 v[34:35], v[8:9], v[170:171], v[34:35] op_sel_hi:[0,1,1]
	v_pk_fma_f32 v[36:37], v[8:9], v[172:173], v[36:37] op_sel_hi:[0,1,1]
	v_pk_fma_f32 v[34:35], v[174:175], v[30:31], v[34:35] op_sel_hi:[1,0,1]
	v_pk_fma_f32 v[36:37], v[176:177], v[30:31], v[36:37] op_sel_hi:[1,0,1]
	v_pk_fma_f32 v[34:35], v[186:187], v[6:7], v[34:35] op_sel_hi:[1,0,1]
	v_pk_fma_f32 v[36:37], v[188:189], v[6:7], v[36:37] op_sel_hi:[1,0,1]
; #define LAS __attribute__((address_space(3)))
; #define WY_RDBLK(m_) do { _Pragma("unroll") for (int t_ = 0; t_ <= (m_); ++t_) LB[(m_) & 1][t_] = *(const LAS f32x4*)(lq + (m_) * WY_BS + 4 * t_); } while (0)
; __device__ __forceinline__ int wy_producer_task(const Ctx& c, int l, int tk, WyPre& P, unsigned* head) {
;     ...
;     {
;         f32x4 LB[2][16];
;         const LAS float* lq = LM + q4 * WY_QS;
;     ...
;         WY_RDBLK(0);
; #pragma unroll
;         for (int m = 0; m < 16; ++m) {
;             if (m + 1 < 16) WY_RDBLK(m + 1);
;             __builtin_amdgcn_sched_barrier(0);
;             f32x4 pre = (f32x4){0.f, 0.f, 0.f, 0.f};
; #pragma unroll
;             for (int t = 0; t < m; ++t) pre = LB[m & 1][t] * own[t] + pre;
; #pragma unroll
;             for (int rr = 0; rr < 4; ++rr) {
;                 float acc = ((q4 == rr) ? own[m] : 0.f) - pre[rr];
;                 if (rr > 0) acc = fmaf(-LB[m & 1][m][rr], own[m], acc);
;                 const float x = quad_sum(acc);
;                 own[m] = (q4 == rr) ? x : own[m]; }
;             __builtin_amdgcn_sched_barrier(0);
;         }
;     ...
;     }
;     if (wid < 4) { float* vo = (float*)(AWS + WS_VAL) + (size_t)tk * 4096 + 16 * wid + cc;
; #pragma unroll
;         for (int t = 0; t < 16; ++t) vo[(4 * t + q4) * 64] = own[t]; }
;     else {
; #pragma unroll
;         for (int t = 0; t < 16; ++t) KT[(4 * t + q4) * 65 + 16 * (wid - 4) + cc] = own[t]; }
	v_pk_fma_f32 v[34:35], v[190:191], v[32:33], v[34:35] op_sel_hi:[1,0,1]
	v_cndmask_b32_e64 v7, 0, v4, s[6:7]
	v_sub_f32_e32 v7, v7, v34
	v_cndmask_b32_e32 v9, 0, v4, vcc
	v_sub_f32_e32 v9, v9, v35
	v_add_f32_dpp v7, v7, v7 quad_perm:[1,0,3,2] row_mask:0xf bank_mask:0xf bound_ctrl:1
	v_pk_fma_f32 v[36:37], v[192:193], v[32:33], v[36:37] op_sel_hi:[1,0,1]
	s_nop 0
	v_add_f32_dpp v7, v7, v7 quad_perm:[2,3,0,1] row_mask:0xf bank_mask:0xf bound_ctrl:1
	v_cndmask_b32_e64 v7, v4, v7, s[6:7]
	v_fma_f32 v9, -v195, v7, v9
	s_nop 1
	v_add_f32_dpp v9, v9, v9 quad_perm:[1,0,3,2] row_mask:0xf bank_mask:0xf bound_ctrl:1
	s_nop 1
	v_add_f32_dpp v9, v9, v9 quad_perm:[2,3,0,1] row_mask:0xf bank_mask:0xf bound_ctrl:1
	v_cndmask_b32_e32 v7, v7, v9, vcc
	v_cndmask_b32_e64 v9, 0, v4, s[2:3]
	v_sub_f32_e32 v9, v9, v36
	v_fma_f32 v9, -v196, v7, v9
	v_cndmask_b32_e64 v4, 0, v4, s[4:5]
	v_sub_f32_e32 v4, v4, v37
	v_add_f32_dpp v9, v9, v9 quad_perm:[1,0,3,2] row_mask:0xf bank_mask:0xf bound_ctrl:1
	s_nop 1
	v_add_f32_dpp v9, v9, v9 quad_perm:[2,3,0,1] row_mask:0xf bank_mask:0xf bound_ctrl:1
	v_cndmask_b32_e64 v7, v7, v9, s[2:3]
	v_fma_f32 v4, -v197, v7, v4
	s_nop 1
	v_add_f32_dpp v4, v4, v4 quad_perm:[1,0,3,2] row_mask:0xf bank_mask:0xf bound_ctrl:1
	s_nop 1
	v_add_f32_dpp v4, v4, v4 quad_perm:[2,3,0,1] row_mask:0xf bank_mask:0xf bound_ctrl:1
	v_cndmask_b32_e64 v4, v7, v4, s[4:5]
	v_pk_fma_f32 v[36:37], v[18:19], v[38:39], 0 op_sel_hi:[0,1,0]
	v_pk_fma_f32 v[36:37], v[20:21], v[42:43], v[36:37] op_sel_hi:[0,1,1]
	v_pk_fma_f32 v[34:35], v[18:19], v[40:41], 0 op_sel_hi:[0,1,0]
	s_waitcnt lgkmcnt(13)
	v_pk_fma_f32 v[36:37], v[16:17], v[56:57], v[36:37] op_sel_hi:[0,1,1]
	v_pk_fma_f32 v[34:35], v[20:21], v[44:45], v[34:35] op_sel_hi:[0,1,1]
	s_waitcnt lgkmcnt(12)
	v_pk_fma_f32 v[36:37], v[22:23], v[60:61], v[36:37] op_sel_hi:[0,1,1]
	v_pk_fma_f32 v[34:35], v[16:17], v[58:59], v[34:35] op_sel_hi:[0,1,1]
	s_waitcnt lgkmcnt(11)
	v_pk_fma_f32 v[36:37], v[14:15], v[76:77], v[36:37] op_sel_hi:[0,1,1]
	v_pk_fma_f32 v[34:35], v[22:23], v[62:63], v[34:35] op_sel_hi:[0,1,1]
	s_waitcnt lgkmcnt(10)
	v_pk_fma_f32 v[36:37], v[24:25], v[126:127], v[36:37] op_sel_hi:[0,1,1]
	v_pk_fma_f32 v[34:35], v[14:15], v[78:79], v[34:35] op_sel_hi:[0,1,1]
	s_waitcnt lgkmcnt(9)
	v_pk_fma_f32 v[36:37], v[12:13], v[138:139], v[36:37] op_sel_hi:[0,1,1]
	v_pk_fma_f32 v[34:35], v[24:25], v[128:129], v[34:35] op_sel_hi:[0,1,1]
	s_waitcnt lgkmcnt(8)
	v_pk_fma_f32 v[36:37], v[26:27], v[142:143], v[36:37] op_sel_hi:[0,1,1]
	v_pk_fma_f32 v[34:35], v[12:13], v[140:141], v[34:35] op_sel_hi:[0,1,1]
	s_waitcnt lgkmcnt(7)
	v_pk_fma_f32 v[36:37], v[10:11], v[146:147], v[36:37] op_sel_hi:[0,1,1]
	v_pk_fma_f32 v[34:35], v[26:27], v[144:145], v[34:35] op_sel_hi:[0,1,1]
	s_waitcnt lgkmcnt(6)
	v_pk_fma_f32 v[36:37], v[28:29], v[158:159], v[36:37] op_sel_hi:[0,1,1]
	v_pk_fma_f32 v[34:35], v[10:11], v[148:149], v[34:35] op_sel_hi:[0,1,1]
	s_waitcnt lgkmcnt(5)
	v_pk_fma_f32 v[36:37], v[8:9], v[162:163], v[36:37] op_sel_hi:[0,1,1]
	v_pk_fma_f32 v[34:35], v[28:29], v[160:161], v[34:35] op_sel_hi:[0,1,1]
	s_waitcnt lgkmcnt(4)
	v_pk_fma_f32 v[36:37], v[30:31], v[166:167], v[36:37] op_sel_hi:[0,1,1]
	v_pk_fma_f32 v[34:35], v[8:9], v[164:165], v[34:35] op_sel_hi:[0,1,1]
	s_waitcnt lgkmcnt(3)
	v_pk_fma_f32 v[36:37], v[178:179], v[6:7], v[36:37] op_sel_hi:[1,0,1]
	v_pk_fma_f32 v[34:35], v[30:31], v[168:169], v[34:35] op_sel_hi:[0,1,1]
	s_waitcnt lgkmcnt(2)
	v_pk_fma_f32 v[36:37], v[182:183], v[32:33], v[36:37] op_sel_hi:[1,0,1]
	v_pk_fma_f32 v[34:35], v[180:181], v[6:7], v[34:35] op_sel_hi:[1,0,1]
	s_waitcnt lgkmcnt(1)
	v_pk_fma_f32 v[36:37], v[198:199], v[4:5], v[36:37] op_sel_hi:[1,0,1]
	v_cndmask_b32_e64 v7, 0, v5, s[6:7]
	v_sub_f32_e32 v7, v7, v36
	v_cndmask_b32_e32 v9, 0, v5, vcc
	v_sub_f32_e32 v9, v9, v37
	v_add_f32_dpp v7, v7, v7 quad_perm:[1,0,3,2] row_mask:0xf bank_mask:0xf bound_ctrl:1
	v_pk_fma_f32 v[34:35], v[184:185], v[32:33], v[34:35] op_sel_hi:[1,0,1]
	s_nop 0
	v_add_f32_dpp v7, v7, v7 quad_perm:[2,3,0,1] row_mask:0xf bank_mask:0xf bound_ctrl:1
	v_cndmask_b32_e64 v7, v5, v7, s[6:7]
	s_waitcnt lgkmcnt(0)
	v_fma_f32 v9, -v203, v7, v9
	v_pk_fma_f32 v[34:35], v[200:201], v[4:5], v[34:35] op_sel_hi:[1,0,1]
	s_nop 0
	v_add_f32_dpp v9, v9, v9 quad_perm:[1,0,3,2] row_mask:0xf bank_mask:0xf bound_ctrl:1
	s_nop 1
	v_add_f32_dpp v9, v9, v9 quad_perm:[2,3,0,1] row_mask:0xf bank_mask:0xf bound_ctrl:1
	v_cndmask_b32_e32 v7, v7, v9, vcc
	v_cndmask_b32_e64 v9, 0, v5, s[2:3]
	v_sub_f32_e32 v9, v9, v34
	v_fma_f32 v9, -v204, v7, v9
	v_cndmask_b32_e64 v5, 0, v5, s[4:5]
	v_sub_f32_e32 v5, v5, v35
	v_add_f32_dpp v9, v9, v9 quad_perm:[1,0,3,2] row_mask:0xf bank_mask:0xf bound_ctrl:1
	s_nop 1
	v_add_f32_dpp v9, v9, v9 quad_perm:[2,3,0,1] row_mask:0xf bank_mask:0xf bound_ctrl:1
	v_cndmask_b32_e64 v7, v7, v9, s[2:3]
	v_fma_f32 v5, -v205, v7, v5
	s_nop 1
	v_add_f32_dpp v5, v5, v5 quad_perm:[1,0,3,2] row_mask:0xf bank_mask:0xf bound_ctrl:1
	s_nop 1
	v_add_f32_dpp v5, v5, v5 quad_perm:[2,3,0,1] row_mask:0xf bank_mask:0xf bound_ctrl:1
	v_cndmask_b32_e64 v5, v7, v5, s[4:5]
	s_mov_b32 s2, 0x5040100
	s_waitcnt vmcnt(8)
	v_perm_b32 v89, v209, v208, s2
	v_perm_b32 v114, v207, v206, s2
	v_perm_b32 v115, v210, v212, s2
	v_perm_b32 v116, v213, v211, s2
	v_perm_b32 v117, v214, v215, s2
	v_perm_b32 v118, v217, v230, s2
	v_perm_b32 v119, v216, v218, s2
	v_perm_b32 v120, v231, v219, s2
	v_perm_b32 v121, v232, v234, s2
	v_perm_b32 v122, v235, v233, s2
	s_and_b64 vcc, exec, s[40:41]
	s_mov_b64 s[2:3], -1
	s_cbranch_vccnz .LBB0_1089
	ds_write_b32 v3, v18 offset:55552
	ds_write_b32 v3, v20 offset:56592
	ds_write_b32 v3, v16 offset:57632
	ds_write_b32 v3, v22 offset:58672
	ds_write_b32 v3, v14 offset:59712
	ds_write_b32 v3, v24 offset:60752
	ds_write_b32 v3, v12 offset:61792
	ds_write_b32 v3, v26 offset:62832
	ds_write_b32 v3, v10 offset:63872
	ds_write_b32 v3, v28 offset:64912
	v_add_u32_e32 v3, 0xda00, v3
	s_mov_b64 s[2:3], 0
	ds_write_b32 v3, v8 offset:10144
	ds_write_b32 v3, v30 offset:11184
	ds_write_b32 v3, v6 offset:12224
	ds_write_b32 v3, v32 offset:13264
	ds_write_b32 v3, v4 offset:14304
	ds_write_b32 v3, v5 offset:15344

; __device__ __forceinline__ float sigmoidf_(float x) { return 1.0f / (1.0f + __expf(-x)); }
; __device__ __forceinline__ float softplusf_(float x) { return fmaxf(x, 0.f) + __logf(1.0f + __expf(-fabsf(x))); }
; #define AIN(i) ld_ptr(c.la + 2 * (i))
; __device__ __forceinline__ int wy_producer_task(const Ctx& c, int l, int tk, WyPre& P, unsigned* head) {
;     ...
;     if (wid == 0) { const float al = -__expf(((const float*)AIN(I_ALOG))[l * 8 + hh]), dt = ((const float*)AIN(I_DTB))[l * 8 + hh];
;         float g = al * softplusf_(P.sa + dt);
; #pragma unroll
;         for (int o = 1; o < 64; o <<= 1) { const float t = __shfl_up(g, o); if (lane >= o) g += t; }
;         GC[lane] = g; BE[lane] = sigmoidf_(P.sb); }
.LBB0_1093:
	v_add_u32_e32 v6, -1, v223
	s_mov_b32 s1, 0xbfb8aa3b
	s_waitcnt vmcnt(0)
	v_mul_f32_e32 v2, 0x3fb8aa3b, v249
	v_exp_f32_e32 v2, v2
	v_add_f32_e32 v3, v111, v250
	v_max_f32_e32 v4, 0, v3
	v_mul_f32_e64 v3, |v3|, s1
	v_exp_f32_e32 v3, v3
	s_mov_b32 s1, 0x800000
	v_add_f32_e32 v3, 1.0, v3
	v_cmp_gt_f32_e32 vcc, s1, v3
	s_mov_b32 s1, 0x3f317217
	s_nop 0
	v_cndmask_b32_e64 v5, 0, 32, vcc
	v_ldexp_f32 v3, v3, v5
	v_log_f32_e32 v3, v3
	s_nop 0
	v_mul_f32_e32 v5, 0x3f317217, v3
	v_fma_f32 v5, v3, s1, -v5
	v_fmac_f32_e32 v5, 0x3377d1cf, v3
	s_mov_b32 s1, 0x7f800000
	v_fmac_f32_e32 v5, 0x3f317217, v3
	v_cmp_lt_f32_e64 s[2:3], |v3|, s1
	s_nop 1
	v_cndmask_b32_e64 v3, v3, v5, s[2:3]
	v_mov_b32_e32 v5, 0x41b17218
	v_cndmask_b32_e32 v5, 0, v5, vcc
	v_sub_f32_e32 v3, v3, v5
	v_and_b32_e32 v5, 64, v223
	v_cmp_lt_i32_e32 vcc, v6, v5
	v_add_f32_e32 v3, v4, v3
	v_mul_f32_e64 v4, v3, -v2
	v_cndmask_b32_e32 v6, v6, v223, vcc
	v_lshlrev_b32_e32 v6, 2, v6
	ds_bpermute_b32 v6, v6, v4
	v_cmp_gt_i32_e32 vcc, 1, v88
	s_waitcnt lgkmcnt(0)
	v_fma_f32 v2, v3, -v2, v6
	v_add_u32_e32 v3, -2, v223
	v_cndmask_b32_e32 v2, v2, v4, vcc
	v_cmp_lt_i32_e32 vcc, v3, v5
	s_nop 1
	v_cndmask_b32_e32 v3, v3, v223, vcc
	v_lshlrev_b32_e32 v3, 2, v3
	ds_bpermute_b32 v3, v3, v2
	v_cmp_gt_i32_e32 vcc, 2, v88
	s_waitcnt lgkmcnt(0)
	v_add_f32_e32 v3, v2, v3
	v_cndmask_b32_e32 v2, v3, v2, vcc
	v_add_u32_e32 v3, -4, v223
	v_cmp_lt_i32_e32 vcc, v3, v5
	s_nop 1
	v_cndmask_b32_e32 v3, v3, v223, vcc
	v_lshlrev_b32_e32 v3, 2, v3
	ds_bpermute_b32 v3, v3, v2
	v_cmp_gt_i32_e32 vcc, 4, v88
	s_waitcnt lgkmcnt(0)
	v_add_f32_e32 v3, v2, v3
	v_cndmask_b32_e32 v2, v3, v2, vcc
	v_add_u32_e32 v3, -8, v223
	v_cmp_lt_i32_e32 vcc, v3, v5
	s_nop 1
	v_cndmask_b32_e32 v3, v3, v223, vcc
	v_lshlrev_b32_e32 v3, 2, v3
	ds_bpermute_b32 v3, v3, v2
	v_cmp_gt_i32_e32 vcc, 8, v88
	s_waitcnt lgkmcnt(0)
	v_add_f32_e32 v3, v2, v3
	v_cndmask_b32_e32 v2, v3, v2, vcc
	v_add_u32_e32 v3, -16, v223
	v_cmp_lt_i32_e32 vcc, v3, v5
	s_nop 1
	v_cndmask_b32_e32 v3, v3, v223, vcc
	v_lshlrev_b32_e32 v3, 2, v3
	ds_bpermute_b32 v3, v3, v2
	v_cmp_gt_i32_e32 vcc, 16, v88
	s_waitcnt lgkmcnt(0)
	v_add_f32_e32 v3, v2, v3
	v_cndmask_b32_e32 v2, v3, v2, vcc
	v_subrev_u32_e32 v3, 32, v223
	v_cmp_lt_i32_e32 vcc, v3, v5
	s_nop 1
	v_cndmask_b32_e32 v3, v3, v223, vcc
	v_lshlrev_b32_e32 v3, 2, v3
	ds_bpermute_b32 v3, v3, v2
	v_cmp_gt_i32_e32 vcc, 32, v88
	s_waitcnt lgkmcnt(0)
	v_add_f32_e32 v3, v2, v3
	v_cndmask_b32_e32 v2, v3, v2, vcc
	v_lshl_add_u32 v3, v88, 2, 0
	v_add_u32_e32 v4, 0x11b00, v3
	ds_write_b32 v4, v2
	v_mul_f32_e32 v2, 0xbfb8aa3b, v109
	v_exp_f32_e32 v2, v2
	v_add_u32_e32 v3, 0x11c00, v3
	v_add_f32_e32 v2, 1.0, v2
	v_div_scale_f32 v4, s[2:3], v2, v2, 1.0
	v_rcp_f32_e32 v5, v4
	s_nop 0
	v_fma_f32 v6, -v4, v5, 1.0
	v_fmac_f32_e32 v5, v6, v5
	v_div_scale_f32 v6, vcc, 1.0, v2, 1.0
	v_mul_f32_e32 v7, v6, v5
	v_fma_f32 v8, -v4, v7, v6
	v_fmac_f32_e32 v7, v8, v5
	v_fma_f32 v4, -v4, v7, v6
	v_div_fmas_f32 v4, v4, v5, v7
	v_div_fixup_f32 v2, v4, v2, 1.0
	ds_write_b32 v3, v2
	s_and_saveexec_b64 s[2:3], s[4:5]
	s_cbranch_execnz .LBB0_966
	s_branch .LBB0_967
